# k-innermost MFMA order in the three GEMM K-loops; s_setprio and the post-barrier lgkmcnt(0) removed from the K-loops; accumulator zeroing with v_mov_b64; row-statistics loads hoisted
# speedup vs baseline: 1.0223x; 1.0105x over previous
; #define PG8_STAGE(bufoff, gbase, voff) do { _Pragma("unroll") for (int _i = 0; _i < 2; ++_i) \
;         __builtin_amdgcn_global_load_lds((const unsigned*)((const char*)(gbase) + (voff)[_i]), (PG8_LAS unsigned*)(lds + (bufoff) + ldsw + _i * 8192), 16, 0, 0); } while (0)
; #define PG8_LDA(dst, b, h) do { _Pragma("unroll") for (int m = 0; m < 4; ++m) _Pragma("unroll") for (int k = 0; k < 2; ++k) dst[m][k] = *(const PG8_LAS bf16x8*)(lds + PG8_SA(b, h) + aoff + m * 2048 + k * 1024); } while (0)
; #define PG8_LDB(dst, b, h) do { _Pragma("unroll") for (int n = 0; n < 2; ++n) _Pragma("unroll") for (int k = 0; k < 2; ++k) dst[n][k] = *(const PG8_LAS bf16x8*)(lds + PG8_SB(b, h) + boff + n * 2048 + k * 1024); } while (0)
; #define PG8_MMA(ai, bj, At, Bt) do { __builtin_amdgcn_s_setprio(1); _Pragma("unroll") for (int m = 0; m < 4; ++m) _Pragma("unroll") for (int n = 0; n < 2; ++n) _Pragma("unroll") for (int k = 0; k < 2; ++k) \
;         acc[ai][bj][m][n] = __builtin_amdgcn_mfma_f32_16x16x32_bf16(Bt[n][k], At[m][k], acc[ai][bj][m][n], 0, 0, 0); __builtin_amdgcn_s_setprio(0); } while (0)
; #define PG8_WAIT_V(n) asm volatile("s_waitcnt vmcnt(" #n ")" ::: "memory")
; template <class Epi, class Sched, bool ALIGN_EPI = false, bool SP2 = false>
; __device__ __forceinline__ void gemm_phase(PG8_LAS unsigned char* lds, const Gemm g, const Sched& S, const Epi& E, const int tid_in) {
;     ...
;             const bool last = (t == nt - 2);
;             const char* a1 = cA + (size_t)(t + 1) * kstep;
;             const char* a2 = last ? nA : cA + (size_t)(t + 2) * kstep; const char* b2 = last ? nB : cB + (size_t)(t + 2) * kstep;
;             const char* a3 = a2 + kstep; const char* b3 = b2 + kstep;
;             if (last && has_next) S.a_ready(nxt);
;             if constexpr (SP2) {
;             PG8_LDB(B0, 0, 0); PG8_LDB(B1, 0, 1); PG8_SCHED; PG8_LDA(At, 0, 0); PG8_STAGE(PG8_SA(1, 1), a1 + hstep, voffA);
;             PG8_WAIT_V(8); PG8_WAIT_L(0); PG8_BAR; PG8_MMA(0, 0, At, B0); PG8_MMA(0, 1, At, B1); PG8_BAR; PG8_SCHED;
;     ...
; #pragma unroll
;         for (int a = 0; a < 2; ++a)
; #pragma unroll
;             for (int b = 0; b < 2; ++b)
; #pragma unroll
;                 for (int m = 0; m < 4; ++m)
; #pragma unroll
;                     for (int n = 0; n < 2; ++n) acc[a][b][m][n] = (f32x4){0.f, 0.f, 0.f, 0.f};
;         cur = nxt; cA = nA; cB = nB; ++ui;
.LBB0_92:
	s_ashr_i32 s25, s24, 31
	s_lshl_b64 s[16:17], s[24:25], 19
	s_add_u32 s34, s84, s16
	s_addc_u32 s35, s85, s17
	s_and_b64 s[16:17], s[36:37], exec
	s_cselect_b32 s11, s35, s15
	s_cselect_b32 s16, s34, s14
	s_ashr_i32 s21, s20, 31
	s_lshl_b64 s[40:41], s[20:21], 19
	s_add_u32 s40, s3, s40
	s_addc_u32 s41, s18, s41
	s_and_b64 s[42:43], s[36:37], exec
	s_cselect_b32 s17, s41, s13
	s_cselect_b32 s21, s40, s12
	s_add_u32 s42, s14, 0x40080
	s_addc_u32 s43, s15, 0
	s_add_u32 s25, s12, 0x100
	v_mov_b32_e32 v6, 0
	s_addc_u32 s39, s13, 0
	s_mov_b32 s45, -2
	v_mov_b32_e32 v7, v6
	v_mov_b64_e32 v[8:9], 0
	v_mov_b64_e32 v[10:11], 0
	v_mov_b64_e32 v[12:13], 0
	v_mov_b64_e32 v[22:23], 0
	v_mov_b64_e32 v[24:25], 0
	v_mov_b64_e32 v[26:27], 0
	v_mov_b64_e32 v[28:29], 0
	v_mov_b64_e32 v[38:39], 0
	v_mov_b64_e32 v[40:41], 0
	v_mov_b64_e32 v[42:43], 0
	v_mov_b64_e32 v[44:45], 0
	v_mov_b64_e32 v[54:55], 0
	v_mov_b64_e32 v[56:57], 0
	v_mov_b64_e32 v[58:59], 0
	v_mov_b64_e32 v[60:61], 0
	v_mov_b64_e32 v[14:15], 0
	v_mov_b64_e32 v[16:17], 0
	v_mov_b64_e32 v[18:19], 0
	v_mov_b64_e32 v[20:21], 0
	v_mov_b64_e32 v[30:31], 0
	v_mov_b64_e32 v[32:33], 0
	v_mov_b64_e32 v[34:35], 0
	v_mov_b64_e32 v[36:37], 0
	v_mov_b64_e32 v[46:47], 0
	v_mov_b64_e32 v[48:49], 0
	v_mov_b64_e32 v[50:51], 0
	v_mov_b64_e32 v[52:53], 0
	v_mov_b64_e32 v[62:63], 0
	v_mov_b64_e32 v[64:65], 0
	v_mov_b64_e32 v[66:67], 0
	v_mov_b64_e32 v[68:69], 0
	v_mov_b64_e32 v[70:71], 0
	v_mov_b64_e32 v[72:73], 0
	v_mov_b64_e32 v[74:75], 0
	v_mov_b64_e32 v[76:77], 0
	v_mov_b64_e32 v[86:87], 0
	v_mov_b64_e32 v[88:89], 0
	v_mov_b64_e32 v[90:91], 0
	v_mov_b64_e32 v[92:93], 0
	v_mov_b64_e32 v[102:103], 0
	v_mov_b64_e32 v[104:105], 0
	v_mov_b64_e32 v[106:107], 0
	v_mov_b64_e32 v[108:109], 0
	v_mov_b64_e32 v[118:119], 0
	v_mov_b64_e32 v[120:121], 0
	v_mov_b64_e32 v[122:123], 0
	v_mov_b64_e32 v[124:125], 0
	v_mov_b64_e32 v[78:79], 0
	v_mov_b64_e32 v[80:81], 0
	v_mov_b64_e32 v[82:83], 0
	v_mov_b64_e32 v[84:85], 0
	v_mov_b64_e32 v[94:95], 0
	v_mov_b64_e32 v[96:97], 0
	v_mov_b64_e32 v[98:99], 0
	v_mov_b64_e32 v[100:101], 0
	v_mov_b64_e32 v[110:111], 0
	v_mov_b64_e32 v[112:113], 0
	v_mov_b64_e32 v[114:115], 0
	v_mov_b64_e32 v[116:117], 0
	v_mov_b64_e32 v[126:127], 0
	v_mov_b64_e32 v[128:129], 0
	v_mov_b64_e32 v[130:131], 0
	v_mov_b64_e32 v[132:133], 0
.LBB0_93:
	s_add_u32 s12, s42, 0xfffc0080
	s_addc_u32 s13, s43, -1
	s_add_i32 s46, 0, 0x10000
	s_cmp_eq_u32 s45, 12
	s_cselect_b32 s15, s11, s13
	s_cselect_b32 s14, s16, s12
	v_add_u32_e32 v148, s46, v150
	s_cselect_b32 s13, s17, s39
	s_cselect_b32 s12, s21, s25
	s_add_i32 s48, 0, 0x14000
	ds_read_b128 v[144:147], v148
	ds_read_b128 v[154:157], v148 offset:1024
	ds_read_b128 v[158:161], v148 offset:2048
	ds_read_b128 v[162:165], v148 offset:3072
	v_add_u32_e32 v148, s48, v150
	ds_read_b128 v[166:169], v148
	ds_read_b128 v[170:173], v148 offset:1024
	ds_read_b128 v[174:177], v148 offset:2048
	ds_read_b128 v[178:181], v148 offset:3072
	v_lshl_add_u64 v[148:149], s[42:43], 0, v[140:141]
	s_add_i32 m0, s22, 0xc000
	ds_read_b128 v[182:185], v152
	ds_read_b128 v[186:189], v152 offset:1024
	ds_read_b128 v[190:193], v152 offset:2048
	ds_read_b128 v[198:201], v152 offset:3072
	ds_read_b128 v[202:205], v152 offset:4096
	ds_read_b128 v[206:209], v152 offset:5120
	ds_read_b128 v[210:213], v152 offset:6144
	ds_read_b128 v[214:217], v152 offset:7168
	global_load_lds_dwordx4 v[148:149], off
	v_lshl_add_u64 v[148:149], s[42:43], 0, v[142:143]
	s_add_i32 m0, s22, 0xe000
	s_nop 0
	global_load_lds_dwordx4 v[148:149], off
	s_waitcnt vmcnt(8)
	s_waitcnt lgkmcnt(0)
	s_barrier
	v_mfma_f32_16x16x32_bf16 v[130:133], v[144:147], v[182:185], v[130:133]
	v_mfma_f32_16x16x32_bf16 v[130:133], v[154:157], v[186:189], v[130:133]
	v_mfma_f32_16x16x32_bf16 v[114:117], v[144:147], v[190:193], v[114:117]
	v_mfma_f32_16x16x32_bf16 v[114:117], v[154:157], v[198:201], v[114:117]
	v_mfma_f32_16x16x32_bf16 v[98:101], v[144:147], v[202:205], v[98:101]
	v_mfma_f32_16x16x32_bf16 v[98:101], v[154:157], v[206:209], v[98:101]
	v_mfma_f32_16x16x32_bf16 v[82:85], v[144:147], v[210:213], v[82:85]
	v_mfma_f32_16x16x32_bf16 v[82:85], v[154:157], v[214:217], v[82:85]
	v_mfma_f32_16x16x32_bf16 v[126:129], v[158:161], v[182:185], v[126:129]
	v_mfma_f32_16x16x32_bf16 v[126:129], v[162:165], v[186:189], v[126:129]
	v_mfma_f32_16x16x32_bf16 v[110:113], v[158:161], v[190:193], v[110:113]
	v_mfma_f32_16x16x32_bf16 v[110:113], v[162:165], v[198:201], v[110:113]
	v_mfma_f32_16x16x32_bf16 v[94:97], v[158:161], v[202:205], v[94:97]
	v_mfma_f32_16x16x32_bf16 v[94:97], v[162:165], v[206:209], v[94:97]
	v_mfma_f32_16x16x32_bf16 v[78:81], v[158:161], v[210:213], v[78:81]
	v_mfma_f32_16x16x32_bf16 v[78:81], v[162:165], v[214:217], v[78:81]
	v_mfma_f32_16x16x32_bf16 v[122:125], v[166:169], v[182:185], v[122:125]
	v_mfma_f32_16x16x32_bf16 v[122:125], v[170:173], v[186:189], v[122:125]
	v_mfma_f32_16x16x32_bf16 v[106:109], v[166:169], v[190:193], v[106:109]
	v_mfma_f32_16x16x32_bf16 v[106:109], v[170:173], v[198:201], v[106:109]
	v_mfma_f32_16x16x32_bf16 v[90:93], v[166:169], v[202:205], v[90:93]
	v_mfma_f32_16x16x32_bf16 v[90:93], v[170:173], v[206:209], v[90:93]
	v_mfma_f32_16x16x32_bf16 v[74:77], v[166:169], v[210:213], v[74:77]
	v_mfma_f32_16x16x32_bf16 v[74:77], v[170:173], v[214:217], v[74:77]
	v_mfma_f32_16x16x32_bf16 v[118:121], v[174:177], v[182:185], v[118:121]
	v_mfma_f32_16x16x32_bf16 v[118:121], v[178:181], v[186:189], v[118:121]
	v_mfma_f32_16x16x32_bf16 v[102:105], v[174:177], v[190:193], v[102:105]
	v_mfma_f32_16x16x32_bf16 v[102:105], v[178:181], v[198:201], v[102:105]
	v_mfma_f32_16x16x32_bf16 v[86:89], v[174:177], v[202:205], v[86:89]
	v_mfma_f32_16x16x32_bf16 v[86:89], v[178:181], v[206:209], v[86:89]
	v_mfma_f32_16x16x32_bf16 v[70:73], v[174:177], v[210:213], v[70:73]
	v_mfma_f32_16x16x32_bf16 v[70:73], v[178:181], v[214:217], v[70:73]
	s_barrier
; #define PG8_STAGE(bufoff, gbase, voff) do { _Pragma("unroll") for (int _i = 0; _i < 2; ++_i) \
;         __builtin_amdgcn_global_load_lds((const unsigned*)((const char*)(gbase) + (voff)[_i]), (PG8_LAS unsigned*)(lds + (bufoff) + ldsw + _i * 8192), 16, 0, 0); } while (0)
; #define PG8_LDA(dst, b, h) do { _Pragma("unroll") for (int m = 0; m < 4; ++m) _Pragma("unroll") for (int k = 0; k < 2; ++k) dst[m][k] = *(const PG8_LAS bf16x8*)(lds + PG8_SA(b, h) + aoff + m * 2048 + k * 1024); } while (0)
; #define PG8_LDB(dst, b, h) do { _Pragma("unroll") for (int n = 0; n < 2; ++n) _Pragma("unroll") for (int k = 0; k < 2; ++k) dst[n][k] = *(const PG8_LAS bf16x8*)(lds + PG8_SB(b, h) + boff + n * 2048 + k * 1024); } while (0)
; #define PG8_MMA(ai, bj, At, Bt) do { __builtin_amdgcn_s_setprio(1); _Pragma("unroll") for (int m = 0; m < 4; ++m) _Pragma("unroll") for (int n = 0; n < 2; ++n) _Pragma("unroll") for (int k = 0; k < 2; ++k) \
;         acc[ai][bj][m][n] = __builtin_amdgcn_mfma_f32_16x16x32_bf16(Bt[n][k], At[m][k], acc[ai][bj][m][n], 0, 0, 0); __builtin_amdgcn_s_setprio(0); } while (0)
; #define PG8_WAIT_V(n) asm volatile("s_waitcnt vmcnt(" #n ")" ::: "memory")
; #define PG8_WAIT_L(n) asm volatile("s_waitcnt lgkmcnt(" #n ")" ::: "memory")
; #define PG8_BAR __builtin_amdgcn_s_barrier()
; #define PG8_SCHED __builtin_amdgcn_sched_barrier(0)
; template <class Epi, class Sched, bool ALIGN_EPI = false, bool SP2 = false>
; __device__ __forceinline__ void gemm_phase(PG8_LAS unsigned char* lds, const Gemm g, const Sched& S, const Epi& E, const int tid_in) {
;     ...
;             PG8_LDA(At, 0, 1); PG8_STAGE(PG8_SB(0, 0), b2, voffB); PG8_STAGE(PG8_SB(0, 1), b2 + hstep, voffB); PG8_STAGE(PG8_SA(0, 0), a2, voffA);
;             PG8_WAIT_V(8); PG8_WAIT_L(0); PG8_BAR; PG8_MMA(1, 0, At, B0); PG8_MMA(1, 1, At, B1); PG8_BAR; PG8_SCHED;
;             PG8_LDB(B0, 1, 0); PG8_LDB(B1, 1, 1); PG8_SCHED; PG8_LDA(At, 1, 0); PG8_STAGE(PG8_SA(0, 1), a2 + hstep, voffA);
;             PG8_WAIT_V(8); PG8_WAIT_L(0); PG8_BAR; PG8_MMA(0, 0, At, B0); PG8_MMA(0, 1, At, B1); PG8_BAR; PG8_SCHED;
	s_add_i32 s46, s46, s19
	v_lshl_add_u64 v[148:149], s[12:13], 0, v[134:135]
	s_mov_b32 m0, s46
	ds_read_b128 v[182:185], v152 offset:16384
	ds_read_b128 v[186:189], v152 offset:17408
	ds_read_b128 v[190:193], v152 offset:18432
	ds_read_b128 v[198:201], v152 offset:19456
	ds_read_b128 v[202:205], v152 offset:20480
	ds_read_b128 v[206:209], v152 offset:21504
	ds_read_b128 v[210:213], v152 offset:22528
	ds_read_b128 v[214:217], v152 offset:23552
	global_load_lds_dwordx4 v[148:149], off
	s_add_i32 m0, s46, 0x2000
	s_add_u32 s46, s12, 0x40000
	v_lshl_add_u64 v[218:219], s[12:13], 0, v[138:139]
	s_addc_u32 s47, s13, 0
	s_add_i32 s48, s48, s19
	global_load_lds_dwordx4 v[218:219], off
	v_lshl_add_u64 v[220:221], s[46:47], 0, v[134:135]
	s_mov_b32 m0, s48
	v_lshl_add_u64 v[222:223], s[14:15], 0, v[136:137]
	global_load_lds_dwordx4 v[220:221], off
	v_lshl_add_u64 v[220:221], s[46:47], 0, v[138:139]
	s_add_i32 m0, s48, 0x2000
	s_nop 0
	global_load_lds_dwordx4 v[220:221], off
	v_lshl_add_u64 v[220:221], s[14:15], 0, v[2:3]
	s_mov_b32 m0, s22
	s_nop 0
	global_load_lds_dwordx4 v[220:221], off
	s_mov_b32 m0, s23
	s_nop 0
	global_load_lds_dwordx4 v[222:223], off
	s_waitcnt vmcnt(8)
	s_waitcnt lgkmcnt(0)
	s_barrier
	v_mfma_f32_16x16x32_bf16 v[66:69], v[144:147], v[182:185], v[66:69]
	v_mfma_f32_16x16x32_bf16 v[66:69], v[154:157], v[186:189], v[66:69]
	v_mfma_f32_16x16x32_bf16 v[50:53], v[144:147], v[190:193], v[50:53]
	v_mfma_f32_16x16x32_bf16 v[50:53], v[154:157], v[198:201], v[50:53]
	v_mfma_f32_16x16x32_bf16 v[34:37], v[144:147], v[202:205], v[34:37]
	v_mfma_f32_16x16x32_bf16 v[34:37], v[154:157], v[206:209], v[34:37]
	v_mfma_f32_16x16x32_bf16 v[18:21], v[144:147], v[210:213], v[18:21]
	v_mfma_f32_16x16x32_bf16 v[18:21], v[154:157], v[214:217], v[18:21]
	v_mfma_f32_16x16x32_bf16 v[62:65], v[158:161], v[182:185], v[62:65]
	v_mfma_f32_16x16x32_bf16 v[62:65], v[162:165], v[186:189], v[62:65]
	v_mfma_f32_16x16x32_bf16 v[46:49], v[158:161], v[190:193], v[46:49]
	v_mfma_f32_16x16x32_bf16 v[46:49], v[162:165], v[198:201], v[46:49]
	v_mfma_f32_16x16x32_bf16 v[30:33], v[158:161], v[202:205], v[30:33]
	v_mfma_f32_16x16x32_bf16 v[30:33], v[162:165], v[206:209], v[30:33]
	v_mfma_f32_16x16x32_bf16 v[14:17], v[158:161], v[210:213], v[14:17]
	v_mfma_f32_16x16x32_bf16 v[14:17], v[162:165], v[214:217], v[14:17]
	v_mfma_f32_16x16x32_bf16 v[58:61], v[166:169], v[182:185], v[58:61]
	v_mfma_f32_16x16x32_bf16 v[58:61], v[170:173], v[186:189], v[58:61]
	v_mfma_f32_16x16x32_bf16 v[42:45], v[166:169], v[190:193], v[42:45]
	v_mfma_f32_16x16x32_bf16 v[42:45], v[170:173], v[198:201], v[42:45]
	v_mfma_f32_16x16x32_bf16 v[26:29], v[166:169], v[202:205], v[26:29]
	v_mfma_f32_16x16x32_bf16 v[26:29], v[170:173], v[206:209], v[26:29]
	v_mfma_f32_16x16x32_bf16 v[10:13], v[166:169], v[210:213], v[10:13]
	v_mfma_f32_16x16x32_bf16 v[10:13], v[170:173], v[214:217], v[10:13]
	v_mfma_f32_16x16x32_bf16 v[54:57], v[174:177], v[182:185], v[54:57]
	v_mfma_f32_16x16x32_bf16 v[54:57], v[178:181], v[186:189], v[54:57]
	v_mfma_f32_16x16x32_bf16 v[38:41], v[174:177], v[190:193], v[38:41]
	v_mfma_f32_16x16x32_bf16 v[38:41], v[178:181], v[198:201], v[38:41]
	v_mfma_f32_16x16x32_bf16 v[22:25], v[174:177], v[202:205], v[22:25]
	v_mfma_f32_16x16x32_bf16 v[22:25], v[178:181], v[206:209], v[22:25]
	v_mfma_f32_16x16x32_bf16 v[6:9], v[174:177], v[210:213], v[6:9]
	v_mfma_f32_16x16x32_bf16 v[6:9], v[178:181], v[214:217], v[6:9]
	s_barrier
	s_add_i32 s46, 0, 0x18000
	v_add_u32_e32 v153, s46, v150
	s_add_i32 s47, 0, 0x1c000
	ds_read_b128 v[144:147], v153
	ds_read_b128 v[154:157], v153 offset:1024
	ds_read_b128 v[158:161], v153 offset:2048
	ds_read_b128 v[162:165], v153 offset:3072
	v_add_u32_e32 v153, s47, v150
	ds_read_b128 v[166:169], v153
	ds_read_b128 v[170:173], v153 offset:1024
	ds_read_b128 v[174:177], v153 offset:2048
	ds_read_b128 v[178:181], v153 offset:3072
	s_add_u32 s14, s14, 0x40000
	s_addc_u32 s15, s15, 0
	s_mov_b32 m0, s26
	v_lshl_add_u64 v[224:225], s[14:15], 0, v[2:3]
	ds_read_b128 v[182:185], v152 offset:32768
	ds_read_b128 v[186:189], v152 offset:33792
	ds_read_b128 v[190:193], v152 offset:34816
	ds_read_b128 v[198:201], v152 offset:35840
	ds_read_b128 v[202:205], v152 offset:36864
	ds_read_b128 v[206:209], v152 offset:37888
	ds_read_b128 v[210:213], v152 offset:38912
	ds_read_b128 v[214:217], v152 offset:39936
	global_load_lds_dwordx4 v[224:225], off
	v_lshl_add_u64 v[224:225], s[14:15], 0, v[136:137]
	s_mov_b32 m0, s27
	s_nop 0
	global_load_lds_dwordx4 v[224:225], off
	s_waitcnt vmcnt(8)
	s_waitcnt lgkmcnt(0)
	s_barrier
; #define PG8_STAGE(bufoff, gbase, voff) do { _Pragma("unroll") for (int _i = 0; _i < 2; ++_i) \
;         __builtin_amdgcn_global_load_lds((const unsigned*)((const char*)(gbase) + (voff)[_i]), (PG8_LAS unsigned*)(lds + (bufoff) + ldsw + _i * 8192), 16, 0, 0); } while (0)
; #define PG8_LDA(dst, b, h) do { _Pragma("unroll") for (int m = 0; m < 4; ++m) _Pragma("unroll") for (int k = 0; k < 2; ++k) dst[m][k] = *(const PG8_LAS bf16x8*)(lds + PG8_SA(b, h) + aoff + m * 2048 + k * 1024); } while (0)
; #define PG8_MMA(ai, bj, At, Bt) do { __builtin_amdgcn_s_setprio(1); _Pragma("unroll") for (int m = 0; m < 4; ++m) _Pragma("unroll") for (int n = 0; n < 2; ++n) _Pragma("unroll") for (int k = 0; k < 2; ++k) \
;         acc[ai][bj][m][n] = __builtin_amdgcn_mfma_f32_16x16x32_bf16(Bt[n][k], At[m][k], acc[ai][bj][m][n], 0, 0, 0); __builtin_amdgcn_s_setprio(0); } while (0)
; #define PG8_WAIT_V(n) asm volatile("s_waitcnt vmcnt(" #n ")" ::: "memory")
; #define PG8_WAIT_L(n) asm volatile("s_waitcnt lgkmcnt(" #n ")" ::: "memory")
; #define PG8_BAR __builtin_amdgcn_s_barrier()
; #define PG8_SCHED __builtin_amdgcn_sched_barrier(0)
; template <class Epi, class Sched, bool ALIGN_EPI = false, bool SP2 = false>
; __device__ __forceinline__ void gemm_phase(PG8_LAS unsigned char* lds, const Gemm g, const Sched& S, const Epi& E, const int tid_in) {
;     ...
;             PG8_WAIT_V(8); PG8_WAIT_L(0); PG8_BAR; PG8_MMA(0, 0, At, B0); PG8_MMA(0, 1, At, B1); PG8_BAR; PG8_SCHED;
;             PG8_LDA(At, 1, 1); PG8_STAGE(PG8_SB(1, 0), b3, voffB); PG8_STAGE(PG8_SB(1, 1), b3 + hstep, voffB); PG8_STAGE(PG8_SA(1, 0), a3, voffA);
;             PG8_WAIT_V(8); PG8_WAIT_L(0); PG8_BAR; PG8_MMA(1, 0, At, B0); PG8_MMA(1, 1, At, B1); PG8_BAR; PG8_SCHED;
;     __device__ __forceinline__ void operator()(const f32x4 (&acc)[2][2][4][2], const Unit& u, int wr, int wc, int fr, int fq) const {
;     ...
;         float rs[2][4];
; #pragma unroll
;         for (int ai = 0; ai < 2; ++ai)
; #pragma unroll
;             for (int m = 0; m < 4; ++m) rs[ai][m] = rowss[row0 + ai * HALF + m * 16];
	v_mfma_f32_16x16x32_bf16 v[130:133], v[144:147], v[182:185], v[130:133]
	v_mfma_f32_16x16x32_bf16 v[130:133], v[154:157], v[186:189], v[130:133]
	v_mfma_f32_16x16x32_bf16 v[114:117], v[144:147], v[190:193], v[114:117]
	v_mfma_f32_16x16x32_bf16 v[114:117], v[154:157], v[198:201], v[114:117]
	v_mfma_f32_16x16x32_bf16 v[98:101], v[144:147], v[202:205], v[98:101]
	v_mfma_f32_16x16x32_bf16 v[98:101], v[154:157], v[206:209], v[98:101]
	v_mfma_f32_16x16x32_bf16 v[82:85], v[144:147], v[210:213], v[82:85]
	v_mfma_f32_16x16x32_bf16 v[82:85], v[154:157], v[214:217], v[82:85]
	v_mfma_f32_16x16x32_bf16 v[126:129], v[158:161], v[182:185], v[126:129]
	v_mfma_f32_16x16x32_bf16 v[126:129], v[162:165], v[186:189], v[126:129]
	v_mfma_f32_16x16x32_bf16 v[110:113], v[158:161], v[190:193], v[110:113]
	v_mfma_f32_16x16x32_bf16 v[110:113], v[162:165], v[198:201], v[110:113]
	v_mfma_f32_16x16x32_bf16 v[94:97], v[158:161], v[202:205], v[94:97]
	v_mfma_f32_16x16x32_bf16 v[94:97], v[162:165], v[206:209], v[94:97]
	v_mfma_f32_16x16x32_bf16 v[78:81], v[158:161], v[210:213], v[78:81]
	v_mfma_f32_16x16x32_bf16 v[78:81], v[162:165], v[214:217], v[78:81]
	v_mfma_f32_16x16x32_bf16 v[122:125], v[166:169], v[182:185], v[122:125]
	v_mfma_f32_16x16x32_bf16 v[122:125], v[170:173], v[186:189], v[122:125]
	v_mfma_f32_16x16x32_bf16 v[106:109], v[166:169], v[190:193], v[106:109]
	v_mfma_f32_16x16x32_bf16 v[106:109], v[170:173], v[198:201], v[106:109]
	v_mfma_f32_16x16x32_bf16 v[90:93], v[166:169], v[202:205], v[90:93]
	v_mfma_f32_16x16x32_bf16 v[90:93], v[170:173], v[206:209], v[90:93]
	v_mfma_f32_16x16x32_bf16 v[74:77], v[166:169], v[210:213], v[74:77]
	v_mfma_f32_16x16x32_bf16 v[74:77], v[170:173], v[214:217], v[74:77]
	v_mfma_f32_16x16x32_bf16 v[118:121], v[174:177], v[182:185], v[118:121]
	v_mfma_f32_16x16x32_bf16 v[118:121], v[178:181], v[186:189], v[118:121]
	v_mfma_f32_16x16x32_bf16 v[102:105], v[174:177], v[190:193], v[102:105]
	v_mfma_f32_16x16x32_bf16 v[102:105], v[178:181], v[198:201], v[102:105]
	v_mfma_f32_16x16x32_bf16 v[86:89], v[174:177], v[202:205], v[86:89]
	v_mfma_f32_16x16x32_bf16 v[86:89], v[178:181], v[206:209], v[86:89]
	v_mfma_f32_16x16x32_bf16 v[70:73], v[174:177], v[210:213], v[70:73]
	v_mfma_f32_16x16x32_bf16 v[70:73], v[178:181], v[214:217], v[70:73]
	s_barrier
	s_add_i32 s14, s46, s19
	v_lshl_add_u64 v[148:149], v[148:149], 0, s[28:29]
	s_mov_b32 m0, s14
	ds_read_b128 v[182:185], v152 offset:49152
	ds_read_b128 v[186:189], v152 offset:50176
	ds_read_b128 v[190:193], v152 offset:51200
	ds_read_b128 v[198:201], v152 offset:52224
	ds_read_b128 v[202:205], v152 offset:53248
	ds_read_b128 v[206:209], v152 offset:54272
	ds_read_b128 v[210:213], v152 offset:55296
	ds_read_b128 v[214:217], v152 offset:56320
	global_load_lds_dwordx4 v[148:149], off
	s_add_i32 m0, s14, 0x2000
	s_add_u32 s12, s12, 0x40080
	v_lshl_add_u64 v[148:149], v[218:219], 0, s[28:29]
	s_addc_u32 s13, s13, 0
	s_add_i32 s14, s47, s19
	global_load_lds_dwordx4 v[148:149], off
	v_lshl_add_u64 v[148:149], s[12:13], 0, v[134:135]
	s_mov_b32 m0, s14
	s_nop 0
	global_load_lds_dwordx4 v[148:149], off
	v_lshl_add_u64 v[148:149], s[12:13], 0, v[138:139]
	s_add_i32 m0, s14, 0x2000
	s_nop 0
	global_load_lds_dwordx4 v[148:149], off
	v_lshl_add_u64 v[148:149], v[220:221], 0, s[28:29]
	s_mov_b32 m0, s30
	s_nop 0
	global_load_lds_dwordx4 v[148:149], off
	v_lshl_add_u64 v[148:149], v[222:223], 0, s[28:29]
	s_mov_b32 m0, s31
	s_nop 0
	global_load_lds_dwordx4 v[148:149], off
	s_waitcnt vmcnt(8)
	s_waitcnt lgkmcnt(0)
	s_cmp_lg_u32 s45, 12
	s_cbranch_scc1 .Lrs_in_skip
	v_lshl_add_u32 v148, s38, 8, v5
	v_ashrrev_i32_e32 v149, 31, v148
	v_lshl_add_u64 v[148:149], v[148:149], 2, s[6:7]
	global_load_dword v226, v[148:149], off
	global_load_dword v227, v[148:149], off offset:64
	global_load_dword v228, v[148:149], off offset:128
	global_load_dword v229, v[148:149], off offset:192
	global_load_dword v238, v[148:149], off offset:512
	global_load_dword v239, v[148:149], off offset:576
	global_load_dword v240, v[148:149], off offset:640
	global_load_dword v241, v[148:149], off offset:704
.Lrs_in_skip:
	s_barrier
	v_mfma_f32_16x16x32_bf16 v[66:69], v[144:147], v[182:185], v[66:69]
	v_mfma_f32_16x16x32_bf16 v[66:69], v[154:157], v[186:189], v[66:69]
	v_mfma_f32_16x16x32_bf16 v[50:53], v[144:147], v[190:193], v[50:53]
	v_mfma_f32_16x16x32_bf16 v[50:53], v[154:157], v[198:201], v[50:53]
	v_mfma_f32_16x16x32_bf16 v[34:37], v[144:147], v[202:205], v[34:37]
	v_mfma_f32_16x16x32_bf16 v[34:37], v[154:157], v[206:209], v[34:37]
	v_mfma_f32_16x16x32_bf16 v[18:21], v[144:147], v[210:213], v[18:21]
	v_mfma_f32_16x16x32_bf16 v[18:21], v[154:157], v[214:217], v[18:21]
	v_mfma_f32_16x16x32_bf16 v[62:65], v[158:161], v[182:185], v[62:65]
	v_mfma_f32_16x16x32_bf16 v[62:65], v[162:165], v[186:189], v[62:65]
	v_mfma_f32_16x16x32_bf16 v[46:49], v[158:161], v[190:193], v[46:49]
	v_mfma_f32_16x16x32_bf16 v[46:49], v[162:165], v[198:201], v[46:49]
	v_mfma_f32_16x16x32_bf16 v[30:33], v[158:161], v[202:205], v[30:33]
	v_mfma_f32_16x16x32_bf16 v[30:33], v[162:165], v[206:209], v[30:33]
	v_mfma_f32_16x16x32_bf16 v[14:17], v[158:161], v[210:213], v[14:17]
	v_mfma_f32_16x16x32_bf16 v[14:17], v[162:165], v[214:217], v[14:17]
	v_mfma_f32_16x16x32_bf16 v[58:61], v[166:169], v[182:185], v[58:61]
	v_mfma_f32_16x16x32_bf16 v[58:61], v[170:173], v[186:189], v[58:61]
	v_mfma_f32_16x16x32_bf16 v[42:45], v[166:169], v[190:193], v[42:45]
	v_mfma_f32_16x16x32_bf16 v[42:45], v[170:173], v[198:201], v[42:45]
	v_mfma_f32_16x16x32_bf16 v[26:29], v[166:169], v[202:205], v[26:29]
	v_mfma_f32_16x16x32_bf16 v[26:29], v[170:173], v[206:209], v[26:29]
	v_mfma_f32_16x16x32_bf16 v[10:13], v[166:169], v[210:213], v[10:13]
	v_mfma_f32_16x16x32_bf16 v[10:13], v[170:173], v[214:217], v[10:13]
	v_mfma_f32_16x16x32_bf16 v[54:57], v[174:177], v[182:185], v[54:57]
	v_mfma_f32_16x16x32_bf16 v[54:57], v[178:181], v[186:189], v[54:57]
	v_mfma_f32_16x16x32_bf16 v[38:41], v[174:177], v[190:193], v[38:41]
	v_mfma_f32_16x16x32_bf16 v[38:41], v[178:181], v[198:201], v[38:41]
	v_mfma_f32_16x16x32_bf16 v[22:25], v[174:177], v[202:205], v[22:25]
	v_mfma_f32_16x16x32_bf16 v[22:25], v[178:181], v[206:209], v[22:25]
	v_mfma_f32_16x16x32_bf16 v[6:9], v[174:177], v[210:213], v[6:9]
	v_mfma_f32_16x16x32_bf16 v[6:9], v[178:181], v[214:217], v[6:9]
	s_barrier
	s_add_i32 s45, s45, 2
	s_add_u32 s42, s42, 0x100
	s_addc_u32 s43, s43, 0
	s_add_u32 s25, s25, 0x100
	s_addc_u32 s39, s39, 0
	s_cmp_gt_u32 s45, 13
	s_cbranch_scc0 .LBB0_93
	s_and_b64 vcc, exec, s[8:9]
	s_cbranch_vccz .LBB0_96
	s_barrier

; #define PG8_STAGE(bufoff, gbase, voff) do { _Pragma("unroll") for (int _i = 0; _i < 2; ++_i) \
;         __builtin_amdgcn_global_load_lds((const unsigned*)((const char*)(gbase) + (voff)[_i]), (PG8_LAS unsigned*)(lds + (bufoff) + ldsw + _i * 8192), 16, 0, 0); } while (0)
; #define PG8_LDA(dst, b, h) do { _Pragma("unroll") for (int m = 0; m < 4; ++m) _Pragma("unroll") for (int k = 0; k < 2; ++k) dst[m][k] = *(const PG8_LAS bf16x8*)(lds + PG8_SA(b, h) + aoff + m * 2048 + k * 1024); } while (0)
; #define PG8_LDB(dst, b, h) do { _Pragma("unroll") for (int n = 0; n < 2; ++n) _Pragma("unroll") for (int k = 0; k < 2; ++k) dst[n][k] = *(const PG8_LAS bf16x8*)(lds + PG8_SB(b, h) + boff + n * 2048 + k * 1024); } while (0)
; #define PG8_MMA(ai, bj, At, Bt) do { __builtin_amdgcn_s_setprio(1); _Pragma("unroll") for (int m = 0; m < 4; ++m) _Pragma("unroll") for (int n = 0; n < 2; ++n) _Pragma("unroll") for (int k = 0; k < 2; ++k) \
;         acc[ai][bj][m][n] = __builtin_amdgcn_mfma_f32_16x16x32_bf16(Bt[n][k], At[m][k], acc[ai][bj][m][n], 0, 0, 0); __builtin_amdgcn_s_setprio(0); } while (0)
; #define PG8_WAIT_V(n) asm volatile("s_waitcnt vmcnt(" #n ")" ::: "memory")
; template <class Epi, class Sched, bool ALIGN_EPI = false, bool SP2 = false>
; __device__ __forceinline__ void gemm_phase(PG8_LAS unsigned char* lds, const Gemm g, const Sched& S, const Epi& E, const int tid_in) {
;     ...
;             const bool last = (t == nt - 2);
;             const char* a1 = cA + (size_t)(t + 1) * kstep;
;             const char* a2 = last ? nA : cA + (size_t)(t + 2) * kstep; const char* b2 = last ? nB : cB + (size_t)(t + 2) * kstep;
;             const char* a3 = a2 + kstep; const char* b3 = b2 + kstep;
;             if (last && has_next) S.a_ready(nxt);
;             if constexpr (SP2) {
;             PG8_LDB(B0, 0, 0); PG8_LDB(B1, 0, 1); PG8_SCHED; PG8_LDA(At, 0, 0); PG8_STAGE(PG8_SA(1, 1), a1 + hstep, voffA);
;             PG8_WAIT_V(8); PG8_WAIT_L(0); PG8_BAR; PG8_MMA(0, 0, At, B0); PG8_MMA(0, 1, At, B1); PG8_BAR; PG8_SCHED;
;     ...
; #pragma unroll
;         for (int a = 0; a < 2; ++a)
; #pragma unroll
;             for (int b = 0; b < 2; ++b)
; #pragma unroll
;                 for (int m = 0; m < 4; ++m)
; #pragma unroll
;                     for (int n = 0; n < 2; ++n) acc[a][b][m][n] = (f32x4){0.f, 0.f, 0.f, 0.f};
;         cur = nxt; cA = nA; cB = nB; ++ui;
.LBB0_153:
	s_ashr_i32 s25, s24, 31
	s_lshl_b64 s[14:15], s[24:25], 19
	s_add_u32 s34, s84, s14
	s_addc_u32 s35, s85, s15
	s_and_b64 s[14:15], s[36:37], exec
	s_cselect_b32 s25, s35, s11
	s_cselect_b32 s41, s34, s10
	s_ashr_i32 s21, s20, 31
	s_lshl_b64 s[14:15], s[20:21], 19
	s_add_u32 s38, s3, s14
	s_addc_u32 s39, s16, s15
	s_and_b64 s[14:15], s[36:37], exec
	s_cselect_b32 s21, s39, s13
	s_cselect_b32 s42, s38, s12
	s_add_u32 s10, s10, 0x40080
	s_addc_u32 s11, s11, 0
	s_add_u32 s43, s12, 0x100
	v_mov_b32_e32 v6, 0
	s_addc_u32 s44, s13, 0
	s_mov_b32 s45, -2
	v_mov_b32_e32 v7, v6
	v_mov_b64_e32 v[8:9], 0
	v_mov_b64_e32 v[10:11], 0
	v_mov_b64_e32 v[12:13], 0
	v_mov_b64_e32 v[22:23], 0
	v_mov_b64_e32 v[24:25], 0
	v_mov_b64_e32 v[26:27], 0
	v_mov_b64_e32 v[28:29], 0
	v_mov_b64_e32 v[38:39], 0
	v_mov_b64_e32 v[40:41], 0
	v_mov_b64_e32 v[42:43], 0
	v_mov_b64_e32 v[44:45], 0
	v_mov_b64_e32 v[54:55], 0
	v_mov_b64_e32 v[56:57], 0
	v_mov_b64_e32 v[58:59], 0
	v_mov_b64_e32 v[60:61], 0
	v_mov_b64_e32 v[14:15], 0
	v_mov_b64_e32 v[16:17], 0
	v_mov_b64_e32 v[18:19], 0
	v_mov_b64_e32 v[20:21], 0
	v_mov_b64_e32 v[30:31], 0
	v_mov_b64_e32 v[32:33], 0
	v_mov_b64_e32 v[34:35], 0
	v_mov_b64_e32 v[36:37], 0
	v_mov_b64_e32 v[46:47], 0
	v_mov_b64_e32 v[48:49], 0
	v_mov_b64_e32 v[50:51], 0
	v_mov_b64_e32 v[52:53], 0
	v_mov_b64_e32 v[62:63], 0
	v_mov_b64_e32 v[64:65], 0
	v_mov_b64_e32 v[66:67], 0
	v_mov_b64_e32 v[68:69], 0
	v_mov_b64_e32 v[70:71], 0
	v_mov_b64_e32 v[72:73], 0
	v_mov_b64_e32 v[74:75], 0
	v_mov_b64_e32 v[76:77], 0
	v_mov_b64_e32 v[86:87], 0
	v_mov_b64_e32 v[88:89], 0
	v_mov_b64_e32 v[90:91], 0
	v_mov_b64_e32 v[92:93], 0
	v_mov_b64_e32 v[102:103], 0
	v_mov_b64_e32 v[104:105], 0
	v_mov_b64_e32 v[110:111], 0
	v_mov_b64_e32 v[112:113], 0
	v_mov_b64_e32 v[118:119], 0
	v_mov_b64_e32 v[120:121], 0
	v_mov_b64_e32 v[122:123], 0
	v_mov_b64_e32 v[124:125], 0
	v_mov_b64_e32 v[78:79], 0
	v_mov_b64_e32 v[80:81], 0
	v_mov_b64_e32 v[82:83], 0
	v_mov_b64_e32 v[84:85], 0
	v_mov_b64_e32 v[94:95], 0
	v_mov_b64_e32 v[96:97], 0
	v_mov_b64_e32 v[98:99], 0
	v_mov_b64_e32 v[100:101], 0
	v_mov_b64_e32 v[106:107], 0
	v_mov_b64_e32 v[108:109], 0
	v_mov_b64_e32 v[114:115], 0
	v_mov_b64_e32 v[116:117], 0
	v_mov_b64_e32 v[126:127], 0
	v_mov_b64_e32 v[128:129], 0
	v_mov_b64_e32 v[130:131], 0
	v_mov_b64_e32 v[132:133], 0
.LBB0_154:
	s_add_u32 s12, s10, 0xfffc0080
	s_addc_u32 s13, s11, -1
	s_add_i32 s46, 0, 0x10000
	s_cmp_eq_u32 s45, 12
	s_cselect_b32 s15, s25, s13
	s_cselect_b32 s14, s41, s12
	v_add_u32_e32 v144, s46, v146
	s_cselect_b32 s13, s21, s44
	s_cselect_b32 s12, s42, s43
	s_add_i32 s48, 0, 0x14000
	ds_read_b128 v[150:153], v144
	ds_read_b128 v[154:157], v144 offset:1024
	ds_read_b128 v[158:161], v144 offset:2048
	ds_read_b128 v[162:165], v144 offset:3072
	v_add_u32_e32 v144, s48, v146
	ds_read_b128 v[166:169], v144
	ds_read_b128 v[170:173], v144 offset:1024
	ds_read_b128 v[174:177], v144 offset:2048
	ds_read_b128 v[178:181], v144 offset:3072
	v_lshl_add_u64 v[144:145], s[10:11], 0, v[140:141]
	s_add_i32 m0, s18, 0xc000
	ds_read_b128 v[182:185], v148
	ds_read_b128 v[186:189], v148 offset:1024
	ds_read_b128 v[190:193], v148 offset:2048
	ds_read_b128 v[198:201], v148 offset:3072
	ds_read_b128 v[202:205], v148 offset:4096
	ds_read_b128 v[206:209], v148 offset:5120
	ds_read_b128 v[210:213], v148 offset:6144
	ds_read_b128 v[214:217], v148 offset:7168
	global_load_lds_dwordx4 v[144:145], off
	v_lshl_add_u64 v[144:145], s[10:11], 0, v[142:143]
	s_add_i32 m0, s18, 0xe000
	s_nop 0
	global_load_lds_dwordx4 v[144:145], off
	s_waitcnt vmcnt(8)
	s_waitcnt lgkmcnt(0)
	s_barrier
	v_mfma_f32_16x16x32_bf16 v[130:133], v[150:153], v[182:185], v[130:133]
	v_mfma_f32_16x16x32_bf16 v[130:133], v[154:157], v[186:189], v[130:133]
	v_mfma_f32_16x16x32_bf16 v[114:117], v[150:153], v[190:193], v[114:117]
	v_mfma_f32_16x16x32_bf16 v[114:117], v[154:157], v[198:201], v[114:117]
	v_mfma_f32_16x16x32_bf16 v[98:101], v[150:153], v[202:205], v[98:101]
	v_mfma_f32_16x16x32_bf16 v[98:101], v[154:157], v[206:209], v[98:101]
	v_mfma_f32_16x16x32_bf16 v[82:85], v[150:153], v[210:213], v[82:85]
	v_mfma_f32_16x16x32_bf16 v[82:85], v[154:157], v[214:217], v[82:85]
	v_mfma_f32_16x16x32_bf16 v[126:129], v[158:161], v[182:185], v[126:129]
	v_mfma_f32_16x16x32_bf16 v[126:129], v[162:165], v[186:189], v[126:129]
	v_mfma_f32_16x16x32_bf16 v[106:109], v[158:161], v[190:193], v[106:109]
	v_mfma_f32_16x16x32_bf16 v[106:109], v[162:165], v[198:201], v[106:109]
	v_mfma_f32_16x16x32_bf16 v[94:97], v[158:161], v[202:205], v[94:97]
	v_mfma_f32_16x16x32_bf16 v[94:97], v[162:165], v[206:209], v[94:97]
	v_mfma_f32_16x16x32_bf16 v[78:81], v[158:161], v[210:213], v[78:81]
	v_mfma_f32_16x16x32_bf16 v[78:81], v[162:165], v[214:217], v[78:81]
	v_mfma_f32_16x16x32_bf16 v[122:125], v[166:169], v[182:185], v[122:125]
	v_mfma_f32_16x16x32_bf16 v[122:125], v[170:173], v[186:189], v[122:125]
	v_mfma_f32_16x16x32_bf16 v[110:113], v[166:169], v[190:193], v[110:113]
	v_mfma_f32_16x16x32_bf16 v[110:113], v[170:173], v[198:201], v[110:113]
	v_mfma_f32_16x16x32_bf16 v[90:93], v[166:169], v[202:205], v[90:93]
	v_mfma_f32_16x16x32_bf16 v[90:93], v[170:173], v[206:209], v[90:93]
	v_mfma_f32_16x16x32_bf16 v[74:77], v[166:169], v[210:213], v[74:77]
	v_mfma_f32_16x16x32_bf16 v[74:77], v[170:173], v[214:217], v[74:77]
	v_mfma_f32_16x16x32_bf16 v[118:121], v[174:177], v[182:185], v[118:121]
	v_mfma_f32_16x16x32_bf16 v[118:121], v[178:181], v[186:189], v[118:121]
	v_mfma_f32_16x16x32_bf16 v[102:105], v[174:177], v[190:193], v[102:105]
	v_mfma_f32_16x16x32_bf16 v[102:105], v[178:181], v[198:201], v[102:105]
	v_mfma_f32_16x16x32_bf16 v[86:89], v[174:177], v[202:205], v[86:89]
	v_mfma_f32_16x16x32_bf16 v[86:89], v[178:181], v[206:209], v[86:89]
	v_mfma_f32_16x16x32_bf16 v[70:73], v[174:177], v[210:213], v[70:73]
	v_mfma_f32_16x16x32_bf16 v[70:73], v[178:181], v[214:217], v[70:73]
	s_barrier
; #define PG8_STAGE(bufoff, gbase, voff) do { _Pragma("unroll") for (int _i = 0; _i < 2; ++_i) \
;         __builtin_amdgcn_global_load_lds((const unsigned*)((const char*)(gbase) + (voff)[_i]), (PG8_LAS unsigned*)(lds + (bufoff) + ldsw + _i * 8192), 16, 0, 0); } while (0)
; #define PG8_LDA(dst, b, h) do { _Pragma("unroll") for (int m = 0; m < 4; ++m) _Pragma("unroll") for (int k = 0; k < 2; ++k) dst[m][k] = *(const PG8_LAS bf16x8*)(lds + PG8_SA(b, h) + aoff + m * 2048 + k * 1024); } while (0)
; #define PG8_LDB(dst, b, h) do { _Pragma("unroll") for (int n = 0; n < 2; ++n) _Pragma("unroll") for (int k = 0; k < 2; ++k) dst[n][k] = *(const PG8_LAS bf16x8*)(lds + PG8_SB(b, h) + boff + n * 2048 + k * 1024); } while (0)
; #define PG8_MMA(ai, bj, At, Bt) do { __builtin_amdgcn_s_setprio(1); _Pragma("unroll") for (int m = 0; m < 4; ++m) _Pragma("unroll") for (int n = 0; n < 2; ++n) _Pragma("unroll") for (int k = 0; k < 2; ++k) \
;         acc[ai][bj][m][n] = __builtin_amdgcn_mfma_f32_16x16x32_bf16(Bt[n][k], At[m][k], acc[ai][bj][m][n], 0, 0, 0); __builtin_amdgcn_s_setprio(0); } while (0)
; #define PG8_WAIT_V(n) asm volatile("s_waitcnt vmcnt(" #n ")" ::: "memory")
; #define PG8_WAIT_L(n) asm volatile("s_waitcnt lgkmcnt(" #n ")" ::: "memory")
; #define PG8_BAR __builtin_amdgcn_s_barrier()
; #define PG8_SCHED __builtin_amdgcn_sched_barrier(0)
; template <class Epi, class Sched, bool ALIGN_EPI = false, bool SP2 = false>
; __device__ __forceinline__ void gemm_phase(PG8_LAS unsigned char* lds, const Gemm g, const Sched& S, const Epi& E, const int tid_in) {
;     ...
;             PG8_LDA(At, 0, 1); PG8_STAGE(PG8_SB(0, 0), b2, voffB); PG8_STAGE(PG8_SB(0, 1), b2 + hstep, voffB); PG8_STAGE(PG8_SA(0, 0), a2, voffA);
;             PG8_WAIT_V(8); PG8_WAIT_L(0); PG8_BAR; PG8_MMA(1, 0, At, B0); PG8_MMA(1, 1, At, B1); PG8_BAR; PG8_SCHED;
;             PG8_LDB(B0, 1, 0); PG8_LDB(B1, 1, 1); PG8_SCHED; PG8_LDA(At, 1, 0); PG8_STAGE(PG8_SA(0, 1), a2 + hstep, voffA);
;             PG8_WAIT_V(8); PG8_WAIT_L(0); PG8_BAR; PG8_MMA(0, 0, At, B0); PG8_MMA(0, 1, At, B1); PG8_BAR; PG8_SCHED;
	s_add_i32 s46, s46, s17
	v_lshl_add_u64 v[144:145], s[12:13], 0, v[136:137]
	s_mov_b32 m0, s46
	ds_read_b128 v[182:185], v148 offset:16384
	ds_read_b128 v[186:189], v148 offset:17408
	ds_read_b128 v[190:193], v148 offset:18432
	ds_read_b128 v[198:201], v148 offset:19456
	ds_read_b128 v[202:205], v148 offset:20480
	ds_read_b128 v[206:209], v148 offset:21504
	ds_read_b128 v[210:213], v148 offset:22528
	ds_read_b128 v[214:217], v148 offset:23552
	global_load_lds_dwordx4 v[144:145], off
	s_add_i32 m0, s46, 0x2000
	s_add_u32 s46, s12, 0x40000
	v_lshl_add_u64 v[218:219], s[12:13], 0, v[2:3]
	s_addc_u32 s47, s13, 0
	s_add_i32 s48, s48, s17
	global_load_lds_dwordx4 v[218:219], off
	v_lshl_add_u64 v[220:221], s[46:47], 0, v[136:137]
	s_mov_b32 m0, s48
	v_lshl_add_u64 v[222:223], s[14:15], 0, v[134:135]
	global_load_lds_dwordx4 v[220:221], off
	v_lshl_add_u64 v[220:221], s[46:47], 0, v[2:3]
	s_add_i32 m0, s48, 0x2000
	s_nop 0
	global_load_lds_dwordx4 v[220:221], off
	v_lshl_add_u64 v[220:221], s[14:15], 0, v[138:139]
	s_mov_b32 m0, s18
	s_nop 0
	global_load_lds_dwordx4 v[220:221], off
	s_mov_b32 m0, s19
	s_nop 0
	global_load_lds_dwordx4 v[222:223], off
	s_waitcnt vmcnt(8)
	s_waitcnt lgkmcnt(0)
	s_barrier
	v_mfma_f32_16x16x32_bf16 v[66:69], v[150:153], v[182:185], v[66:69]
	v_mfma_f32_16x16x32_bf16 v[66:69], v[154:157], v[186:189], v[66:69]
	v_mfma_f32_16x16x32_bf16 v[50:53], v[150:153], v[190:193], v[50:53]
	v_mfma_f32_16x16x32_bf16 v[50:53], v[154:157], v[198:201], v[50:53]
	v_mfma_f32_16x16x32_bf16 v[34:37], v[150:153], v[202:205], v[34:37]
	v_mfma_f32_16x16x32_bf16 v[34:37], v[154:157], v[206:209], v[34:37]
	v_mfma_f32_16x16x32_bf16 v[18:21], v[150:153], v[210:213], v[18:21]
	v_mfma_f32_16x16x32_bf16 v[18:21], v[154:157], v[214:217], v[18:21]
	v_mfma_f32_16x16x32_bf16 v[62:65], v[158:161], v[182:185], v[62:65]
	v_mfma_f32_16x16x32_bf16 v[62:65], v[162:165], v[186:189], v[62:65]
	v_mfma_f32_16x16x32_bf16 v[46:49], v[158:161], v[190:193], v[46:49]
	v_mfma_f32_16x16x32_bf16 v[46:49], v[162:165], v[198:201], v[46:49]
	v_mfma_f32_16x16x32_bf16 v[30:33], v[158:161], v[202:205], v[30:33]
	v_mfma_f32_16x16x32_bf16 v[30:33], v[162:165], v[206:209], v[30:33]
	v_mfma_f32_16x16x32_bf16 v[14:17], v[158:161], v[210:213], v[14:17]
	v_mfma_f32_16x16x32_bf16 v[14:17], v[162:165], v[214:217], v[14:17]
	v_mfma_f32_16x16x32_bf16 v[58:61], v[166:169], v[182:185], v[58:61]
	v_mfma_f32_16x16x32_bf16 v[58:61], v[170:173], v[186:189], v[58:61]
	v_mfma_f32_16x16x32_bf16 v[42:45], v[166:169], v[190:193], v[42:45]
	v_mfma_f32_16x16x32_bf16 v[42:45], v[170:173], v[198:201], v[42:45]
	v_mfma_f32_16x16x32_bf16 v[26:29], v[166:169], v[202:205], v[26:29]
	v_mfma_f32_16x16x32_bf16 v[26:29], v[170:173], v[206:209], v[26:29]
	v_mfma_f32_16x16x32_bf16 v[10:13], v[166:169], v[210:213], v[10:13]
	v_mfma_f32_16x16x32_bf16 v[10:13], v[170:173], v[214:217], v[10:13]
	v_mfma_f32_16x16x32_bf16 v[54:57], v[174:177], v[182:185], v[54:57]
	v_mfma_f32_16x16x32_bf16 v[54:57], v[178:181], v[186:189], v[54:57]
	v_mfma_f32_16x16x32_bf16 v[38:41], v[174:177], v[190:193], v[38:41]
	v_mfma_f32_16x16x32_bf16 v[38:41], v[178:181], v[198:201], v[38:41]
	v_mfma_f32_16x16x32_bf16 v[22:25], v[174:177], v[202:205], v[22:25]
	v_mfma_f32_16x16x32_bf16 v[22:25], v[178:181], v[206:209], v[22:25]
	v_mfma_f32_16x16x32_bf16 v[6:9], v[174:177], v[210:213], v[6:9]
	v_mfma_f32_16x16x32_bf16 v[6:9], v[178:181], v[214:217], v[6:9]
	s_barrier
	s_add_i32 s46, 0, 0x18000
	v_add_u32_e32 v149, s46, v146
	s_add_i32 s47, 0, 0x1c000
	ds_read_b128 v[150:153], v149
	ds_read_b128 v[154:157], v149 offset:1024
	ds_read_b128 v[158:161], v149 offset:2048
	ds_read_b128 v[162:165], v149 offset:3072
	v_add_u32_e32 v149, s47, v146
	ds_read_b128 v[166:169], v149
	ds_read_b128 v[170:173], v149 offset:1024
	ds_read_b128 v[174:177], v149 offset:2048
	ds_read_b128 v[178:181], v149 offset:3072
	s_add_u32 s14, s14, 0x40000
	s_addc_u32 s15, s15, 0
	s_mov_b32 m0, s22
	v_lshl_add_u64 v[224:225], s[14:15], 0, v[138:139]
	ds_read_b128 v[182:185], v148 offset:32768
	ds_read_b128 v[186:189], v148 offset:33792
	ds_read_b128 v[190:193], v148 offset:34816
	ds_read_b128 v[198:201], v148 offset:35840
	ds_read_b128 v[202:205], v148 offset:36864
	ds_read_b128 v[206:209], v148 offset:37888
	ds_read_b128 v[210:213], v148 offset:38912
	ds_read_b128 v[214:217], v148 offset:39936
	global_load_lds_dwordx4 v[224:225], off
	v_lshl_add_u64 v[224:225], s[14:15], 0, v[134:135]
	s_mov_b32 m0, s23
	s_nop 0
	global_load_lds_dwordx4 v[224:225], off
	s_waitcnt vmcnt(8)
	s_waitcnt lgkmcnt(0)
	s_barrier
; #define PG8_STAGE(bufoff, gbase, voff) do { _Pragma("unroll") for (int _i = 0; _i < 2; ++_i) \
;         __builtin_amdgcn_global_load_lds((const unsigned*)((const char*)(gbase) + (voff)[_i]), (PG8_LAS unsigned*)(lds + (bufoff) + ldsw + _i * 8192), 16, 0, 0); } while (0)
; #define PG8_LDA(dst, b, h) do { _Pragma("unroll") for (int m = 0; m < 4; ++m) _Pragma("unroll") for (int k = 0; k < 2; ++k) dst[m][k] = *(const PG8_LAS bf16x8*)(lds + PG8_SA(b, h) + aoff + m * 2048 + k * 1024); } while (0)
; #define PG8_MMA(ai, bj, At, Bt) do { __builtin_amdgcn_s_setprio(1); _Pragma("unroll") for (int m = 0; m < 4; ++m) _Pragma("unroll") for (int n = 0; n < 2; ++n) _Pragma("unroll") for (int k = 0; k < 2; ++k) \
;         acc[ai][bj][m][n] = __builtin_amdgcn_mfma_f32_16x16x32_bf16(Bt[n][k], At[m][k], acc[ai][bj][m][n], 0, 0, 0); __builtin_amdgcn_s_setprio(0); } while (0)
; #define PG8_WAIT_V(n) asm volatile("s_waitcnt vmcnt(" #n ")" ::: "memory")
; #define PG8_WAIT_L(n) asm volatile("s_waitcnt lgkmcnt(" #n ")" ::: "memory")
; #define PG8_BAR __builtin_amdgcn_s_barrier()
; #define PG8_SCHED __builtin_amdgcn_sched_barrier(0)
; template <class Epi, class Sched, bool ALIGN_EPI = false, bool SP2 = false>
; __device__ __forceinline__ void gemm_phase(PG8_LAS unsigned char* lds, const Gemm g, const Sched& S, const Epi& E, const int tid_in) {
;     ...
;             PG8_WAIT_V(8); PG8_WAIT_L(0); PG8_BAR; PG8_MMA(0, 0, At, B0); PG8_MMA(0, 1, At, B1); PG8_BAR; PG8_SCHED;
;             PG8_LDA(At, 1, 1); PG8_STAGE(PG8_SB(1, 0), b3, voffB); PG8_STAGE(PG8_SB(1, 1), b3 + hstep, voffB); PG8_STAGE(PG8_SA(1, 0), a3, voffA);
;             PG8_WAIT_V(8); PG8_WAIT_L(0); PG8_BAR; PG8_MMA(1, 0, At, B0); PG8_MMA(1, 1, At, B1); PG8_BAR; PG8_SCHED;
;     __device__ __forceinline__ void operator()(const f32x4 (&acc)[2][2][4][2], const Unit& u, int wr, int wc, int fr, int fq) const {
;     ...
;         float rs[2][4];
; #pragma unroll
;         for (int ai = 0; ai < 2; ++ai)
; #pragma unroll
;             for (int m = 0; m < 4; ++m) rs[ai][m] = rowss[row0 + ai * HALF + m * 16];
	v_mfma_f32_16x16x32_bf16 v[130:133], v[150:153], v[182:185], v[130:133]
	v_mfma_f32_16x16x32_bf16 v[130:133], v[154:157], v[186:189], v[130:133]
	v_mfma_f32_16x16x32_bf16 v[114:117], v[150:153], v[190:193], v[114:117]
	v_mfma_f32_16x16x32_bf16 v[114:117], v[154:157], v[198:201], v[114:117]
	v_mfma_f32_16x16x32_bf16 v[98:101], v[150:153], v[202:205], v[98:101]
	v_mfma_f32_16x16x32_bf16 v[98:101], v[154:157], v[206:209], v[98:101]
	v_mfma_f32_16x16x32_bf16 v[82:85], v[150:153], v[210:213], v[82:85]
	v_mfma_f32_16x16x32_bf16 v[82:85], v[154:157], v[214:217], v[82:85]
	v_mfma_f32_16x16x32_bf16 v[126:129], v[158:161], v[182:185], v[126:129]
	v_mfma_f32_16x16x32_bf16 v[126:129], v[162:165], v[186:189], v[126:129]
	v_mfma_f32_16x16x32_bf16 v[106:109], v[158:161], v[190:193], v[106:109]
	v_mfma_f32_16x16x32_bf16 v[106:109], v[162:165], v[198:201], v[106:109]
	v_mfma_f32_16x16x32_bf16 v[94:97], v[158:161], v[202:205], v[94:97]
	v_mfma_f32_16x16x32_bf16 v[94:97], v[162:165], v[206:209], v[94:97]
	v_mfma_f32_16x16x32_bf16 v[78:81], v[158:161], v[210:213], v[78:81]
	v_mfma_f32_16x16x32_bf16 v[78:81], v[162:165], v[214:217], v[78:81]
	v_mfma_f32_16x16x32_bf16 v[122:125], v[166:169], v[182:185], v[122:125]
	v_mfma_f32_16x16x32_bf16 v[122:125], v[170:173], v[186:189], v[122:125]
	v_mfma_f32_16x16x32_bf16 v[110:113], v[166:169], v[190:193], v[110:113]
	v_mfma_f32_16x16x32_bf16 v[110:113], v[170:173], v[198:201], v[110:113]
	v_mfma_f32_16x16x32_bf16 v[90:93], v[166:169], v[202:205], v[90:93]
	v_mfma_f32_16x16x32_bf16 v[90:93], v[170:173], v[206:209], v[90:93]
	v_mfma_f32_16x16x32_bf16 v[74:77], v[166:169], v[210:213], v[74:77]
	v_mfma_f32_16x16x32_bf16 v[74:77], v[170:173], v[214:217], v[74:77]
	v_mfma_f32_16x16x32_bf16 v[118:121], v[174:177], v[182:185], v[118:121]
	v_mfma_f32_16x16x32_bf16 v[118:121], v[178:181], v[186:189], v[118:121]
	v_mfma_f32_16x16x32_bf16 v[102:105], v[174:177], v[190:193], v[102:105]
	v_mfma_f32_16x16x32_bf16 v[102:105], v[178:181], v[198:201], v[102:105]
	v_mfma_f32_16x16x32_bf16 v[86:89], v[174:177], v[202:205], v[86:89]
	v_mfma_f32_16x16x32_bf16 v[86:89], v[178:181], v[206:209], v[86:89]
	v_mfma_f32_16x16x32_bf16 v[70:73], v[174:177], v[210:213], v[70:73]
	v_mfma_f32_16x16x32_bf16 v[70:73], v[178:181], v[214:217], v[70:73]
	s_barrier
	s_add_i32 s14, s46, s17
	v_lshl_add_u64 v[144:145], v[144:145], 0, s[28:29]
	s_mov_b32 m0, s14
	ds_read_b128 v[182:185], v148 offset:49152
	ds_read_b128 v[186:189], v148 offset:50176
	ds_read_b128 v[190:193], v148 offset:51200
	ds_read_b128 v[198:201], v148 offset:52224
	ds_read_b128 v[202:205], v148 offset:53248
	ds_read_b128 v[206:209], v148 offset:54272
	ds_read_b128 v[210:213], v148 offset:55296
	ds_read_b128 v[214:217], v148 offset:56320
	global_load_lds_dwordx4 v[144:145], off
	s_add_i32 m0, s14, 0x2000
	s_add_u32 s12, s12, 0x40080
	v_lshl_add_u64 v[144:145], v[218:219], 0, s[28:29]
	s_addc_u32 s13, s13, 0
	s_add_i32 s14, s47, s17
	global_load_lds_dwordx4 v[144:145], off
	v_lshl_add_u64 v[144:145], s[12:13], 0, v[136:137]
	s_mov_b32 m0, s14
	s_nop 0
	global_load_lds_dwordx4 v[144:145], off
	v_lshl_add_u64 v[144:145], s[12:13], 0, v[2:3]
	s_add_i32 m0, s14, 0x2000
	s_nop 0
	global_load_lds_dwordx4 v[144:145], off
	v_lshl_add_u64 v[144:145], v[220:221], 0, s[28:29]
	s_mov_b32 m0, s26
	s_nop 0
	global_load_lds_dwordx4 v[144:145], off
	v_lshl_add_u64 v[144:145], v[222:223], 0, s[28:29]
	s_mov_b32 m0, s27
	s_nop 0
	global_load_lds_dwordx4 v[144:145], off
	s_waitcnt vmcnt(8)
	s_waitcnt lgkmcnt(0)
	s_cmp_lg_u32 s45, 12
	s_cbranch_scc1 .Lrs_gu_skip
	v_lshl_add_u32 v144, s40, 8, v5
	v_ashrrev_i32_e32 v145, 31, v144
	v_lshl_add_u64 v[144:145], v[144:145], 2, s[6:7]
	global_load_dword v226, v[144:145], off
	global_load_dword v227, v[144:145], off offset:64
	global_load_dword v228, v[144:145], off offset:128
	global_load_dword v229, v[144:145], off offset:192
	global_load_dword v238, v[144:145], off offset:512
	global_load_dword v239, v[144:145], off offset:576
	global_load_dword v240, v[144:145], off offset:640
	global_load_dword v241, v[144:145], off offset:704
.Lrs_gu_skip:
	s_barrier
	v_mfma_f32_16x16x32_bf16 v[66:69], v[150:153], v[182:185], v[66:69]
	v_mfma_f32_16x16x32_bf16 v[66:69], v[154:157], v[186:189], v[66:69]
	v_mfma_f32_16x16x32_bf16 v[50:53], v[150:153], v[190:193], v[50:53]
	v_mfma_f32_16x16x32_bf16 v[50:53], v[154:157], v[198:201], v[50:53]
	v_mfma_f32_16x16x32_bf16 v[34:37], v[150:153], v[202:205], v[34:37]
	v_mfma_f32_16x16x32_bf16 v[34:37], v[154:157], v[206:209], v[34:37]
	v_mfma_f32_16x16x32_bf16 v[18:21], v[150:153], v[210:213], v[18:21]
	v_mfma_f32_16x16x32_bf16 v[18:21], v[154:157], v[214:217], v[18:21]
	v_mfma_f32_16x16x32_bf16 v[62:65], v[158:161], v[182:185], v[62:65]
	v_mfma_f32_16x16x32_bf16 v[62:65], v[162:165], v[186:189], v[62:65]
	v_mfma_f32_16x16x32_bf16 v[46:49], v[158:161], v[190:193], v[46:49]
	v_mfma_f32_16x16x32_bf16 v[46:49], v[162:165], v[198:201], v[46:49]
	v_mfma_f32_16x16x32_bf16 v[30:33], v[158:161], v[202:205], v[30:33]
	v_mfma_f32_16x16x32_bf16 v[30:33], v[162:165], v[206:209], v[30:33]
	v_mfma_f32_16x16x32_bf16 v[14:17], v[158:161], v[210:213], v[14:17]
	v_mfma_f32_16x16x32_bf16 v[14:17], v[162:165], v[214:217], v[14:17]
	v_mfma_f32_16x16x32_bf16 v[58:61], v[166:169], v[182:185], v[58:61]
	v_mfma_f32_16x16x32_bf16 v[58:61], v[170:173], v[186:189], v[58:61]
	v_mfma_f32_16x16x32_bf16 v[42:45], v[166:169], v[190:193], v[42:45]
	v_mfma_f32_16x16x32_bf16 v[42:45], v[170:173], v[198:201], v[42:45]
	v_mfma_f32_16x16x32_bf16 v[26:29], v[166:169], v[202:205], v[26:29]
	v_mfma_f32_16x16x32_bf16 v[26:29], v[170:173], v[206:209], v[26:29]
	v_mfma_f32_16x16x32_bf16 v[10:13], v[166:169], v[210:213], v[10:13]
	v_mfma_f32_16x16x32_bf16 v[10:13], v[170:173], v[214:217], v[10:13]
	v_mfma_f32_16x16x32_bf16 v[54:57], v[174:177], v[182:185], v[54:57]
	v_mfma_f32_16x16x32_bf16 v[54:57], v[178:181], v[186:189], v[54:57]
	v_mfma_f32_16x16x32_bf16 v[38:41], v[174:177], v[190:193], v[38:41]
	v_mfma_f32_16x16x32_bf16 v[38:41], v[178:181], v[198:201], v[38:41]
	v_mfma_f32_16x16x32_bf16 v[22:25], v[174:177], v[202:205], v[22:25]
	v_mfma_f32_16x16x32_bf16 v[22:25], v[178:181], v[206:209], v[22:25]
	v_mfma_f32_16x16x32_bf16 v[6:9], v[174:177], v[210:213], v[6:9]
	v_mfma_f32_16x16x32_bf16 v[6:9], v[178:181], v[214:217], v[6:9]
	s_barrier
	s_add_i32 s45, s45, 2
	s_add_u32 s10, s10, 0x100
	s_addc_u32 s11, s11, 0
	s_add_u32 s43, s43, 0x100
	s_addc_u32 s44, s44, 0
	s_cmp_gt_u32 s45, 13
	s_cbranch_scc0 .LBB0_154
	s_and_b64 vcc, exec, s[8:9]
	s_cbranch_vccz .LBB0_157
	s_barrier

; #define PG8_STAGE(bufoff, gbase, voff) do { _Pragma("unroll") for (int _i = 0; _i < 2; ++_i) \
;         __builtin_amdgcn_global_load_lds((const unsigned*)((const char*)(gbase) + (voff)[_i]), (PG8_LAS unsigned*)(lds + (bufoff) + ldsw + _i * 8192), 16, 0, 0); } while (0)
; #define PG8_LDA(dst, b, h) do { _Pragma("unroll") for (int m = 0; m < 4; ++m) _Pragma("unroll") for (int k = 0; k < 2; ++k) dst[m][k] = *(const PG8_LAS bf16x8*)(lds + PG8_SA(b, h) + aoff + m * 2048 + k * 1024); } while (0)
; #define PG8_LDB(dst, b, h) do { _Pragma("unroll") for (int n = 0; n < 2; ++n) _Pragma("unroll") for (int k = 0; k < 2; ++k) dst[n][k] = *(const PG8_LAS bf16x8*)(lds + PG8_SB(b, h) + boff + n * 2048 + k * 1024); } while (0)
; #define PG8_MMA(ai, bj, At, Bt) do { __builtin_amdgcn_s_setprio(1); _Pragma("unroll") for (int m = 0; m < 4; ++m) _Pragma("unroll") for (int n = 0; n < 2; ++n) _Pragma("unroll") for (int k = 0; k < 2; ++k) \
;         acc[ai][bj][m][n] = __builtin_amdgcn_mfma_f32_16x16x32_bf16(Bt[n][k], At[m][k], acc[ai][bj][m][n], 0, 0, 0); __builtin_amdgcn_s_setprio(0); } while (0)
; #define PG8_WAIT_V(n) asm volatile("s_waitcnt vmcnt(" #n ")" ::: "memory")
; template <class Epi, class Sched, bool ALIGN_EPI = false, bool SP2 = false>
; __device__ __forceinline__ void gemm_phase(PG8_LAS unsigned char* lds, const Gemm g, const Sched& S, const Epi& E, const int tid_in) {
;     ...
;             const bool last = (t == nt - 2);
;             const char* a1 = cA + (size_t)(t + 1) * kstep;
;             const char* a2 = last ? nA : cA + (size_t)(t + 2) * kstep; const char* b2 = last ? nB : cB + (size_t)(t + 2) * kstep;
;             const char* a3 = a2 + kstep; const char* b3 = b2 + kstep;
;             if (last && has_next) S.a_ready(nxt);
;             if constexpr (SP2) {
;             PG8_LDB(B0, 0, 0); PG8_LDB(B1, 0, 1); PG8_SCHED; PG8_LDA(At, 0, 0); PG8_STAGE(PG8_SA(1, 1), a1 + hstep, voffA);
;             PG8_WAIT_V(8); PG8_WAIT_L(0); PG8_BAR; PG8_MMA(0, 0, At, B0); PG8_MMA(0, 1, At, B1); PG8_BAR; PG8_SCHED;
;     ...
; #pragma unroll
;         for (int a = 0; a < 2; ++a)
; #pragma unroll
;             for (int b = 0; b < 2; ++b)
; #pragma unroll
;                 for (int m = 0; m < 4; ++m)
; #pragma unroll
;                     for (int n = 0; n < 2; ++n) acc[a][b][m][n] = (f32x4){0.f, 0.f, 0.f, 0.f};
;         cur = nxt; cA = nA; cB = nB; ++ui;
.LBB0_176:
	s_add_u32 s10, s10, 0x80
	s_addc_u32 s11, s11, 0
	s_add_u32 s14, s12, 0x100
	v_mov_b32_e32 v6, 0
	s_addc_u32 s15, s13, 0
	s_mov_b32 s12, 0
	v_mov_b32_e32 v7, v6
	v_mov_b64_e32 v[8:9], 0
	v_mov_b64_e32 v[10:11], 0
	v_mov_b32_e32 v12, v6
	s_waitcnt lgkmcnt(0)
	v_mov_b32_e32 v13, v6
	v_mov_b64_e32 v[22:23], 0
	v_mov_b64_e32 v[24:25], 0
	v_mov_b64_e32 v[26:27], 0
	v_mov_b64_e32 v[28:29], 0
	v_mov_b64_e32 v[38:39], 0
	v_mov_b64_e32 v[40:41], 0
	v_mov_b64_e32 v[42:43], 0
	v_mov_b64_e32 v[44:45], 0
	v_mov_b64_e32 v[54:55], 0
	v_mov_b64_e32 v[56:57], 0
	v_mov_b64_e32 v[58:59], 0
	v_mov_b64_e32 v[60:61], 0
	v_mov_b64_e32 v[14:15], 0
	v_mov_b64_e32 v[16:17], 0
	v_mov_b64_e32 v[18:19], 0
	v_mov_b64_e32 v[20:21], 0
	v_mov_b64_e32 v[30:31], 0
	v_mov_b64_e32 v[32:33], 0
	v_mov_b64_e32 v[34:35], 0
	v_mov_b64_e32 v[36:37], 0
	v_mov_b64_e32 v[46:47], 0
	v_mov_b64_e32 v[48:49], 0
	v_mov_b64_e32 v[50:51], 0
	v_mov_b64_e32 v[52:53], 0
	v_mov_b64_e32 v[62:63], 0
	v_mov_b64_e32 v[64:65], 0
	v_mov_b64_e32 v[66:67], 0
	v_mov_b64_e32 v[68:69], 0
	v_mov_b64_e32 v[70:71], 0
	v_mov_b64_e32 v[72:73], 0
	v_mov_b64_e32 v[74:75], 0
	v_mov_b64_e32 v[76:77], 0
	v_mov_b64_e32 v[86:87], 0
	v_mov_b64_e32 v[88:89], 0
	v_mov_b64_e32 v[90:91], 0
	v_mov_b64_e32 v[92:93], 0
	v_mov_b64_e32 v[102:103], 0
	v_mov_b64_e32 v[104:105], 0
	v_mov_b64_e32 v[106:107], 0
	v_mov_b64_e32 v[108:109], 0
	v_mov_b64_e32 v[118:119], 0
	v_mov_b64_e32 v[120:121], 0
	v_mov_b64_e32 v[122:123], 0
	v_mov_b64_e32 v[124:125], 0
	v_mov_b64_e32 v[78:79], 0
	v_mov_b64_e32 v[80:81], 0
	v_mov_b64_e32 v[82:83], 0
	v_mov_b64_e32 v[84:85], 0
	v_mov_b64_e32 v[94:95], 0
	v_mov_b64_e32 v[96:97], 0
	v_mov_b64_e32 v[98:99], 0
	v_mov_b64_e32 v[100:101], 0
	v_mov_b64_e32 v[110:111], 0
	v_mov_b64_e32 v[112:113], 0
	v_mov_b64_e32 v[114:115], 0
	v_mov_b64_e32 v[116:117], 0
	v_mov_b64_e32 v[166:167], 0
	v_mov_b64_e32 v[168:169], 0
	v_mov_b64_e32 v[174:175], 0
	v_mov_b64_e32 v[176:177], 0
.LBB0_177:
	s_add_i32 s51, s12, 2
	s_add_u32 s52, s10, 0x80
	s_addc_u32 s13, s11, 0
	s_add_i32 s54, 0, 0x10000
	s_cmp_eq_u32 s31, s12
	s_cselect_b32 s13, s1, s13
	s_cselect_b32 s12, s0, s52
	s_cselect_b32 s53, s45, s15
	s_cselect_b32 s52, s44, s14
	s_add_i32 s55, 0, 0x14000
	v_add_u32_e32 v138, s54, v247
	v_add_u32_e32 v154, s55, v247
	ds_read_b128 v[126:129], v138
	ds_read_b128 v[130:133], v138 offset:1024
	ds_read_b128 v[134:137], v138 offset:2048
	ds_read_b128 v[138:141], v138 offset:3072
	ds_read_b128 v[142:145], v154
	ds_read_b128 v[146:149], v154 offset:1024
	ds_read_b128 v[150:153], v154 offset:2048
	ds_read_b128 v[154:157], v154 offset:3072
	v_lshl_add_u64 v[214:215], s[10:11], 0, v[206:207]
	s_add_i32 m0, s18, 0xc000
	ds_read_b128 v[158:161], v249
	ds_read_b128 v[162:165], v249 offset:1024
	ds_read_b128 v[170:173], v249 offset:2048
	ds_read_b128 v[178:181], v249 offset:3072
	ds_read_b128 v[182:185], v249 offset:4096
	ds_read_b128 v[186:189], v249 offset:5120
	ds_read_b128 v[190:193], v249 offset:6144
	ds_read_b128 v[210:213], v249 offset:7168
	global_load_lds_dwordx4 v[214:215], off
	v_lshl_add_u64 v[214:215], s[10:11], 0, v[208:209]
	s_add_i32 m0, s18, 0xe000
	s_nop 0
	global_load_lds_dwordx4 v[214:215], off
	s_waitcnt vmcnt(8)
	s_waitcnt lgkmcnt(0)
	s_barrier
	v_mfma_f32_16x16x32_bf16 v[174:177], v[126:129], v[158:161], v[174:177]
	v_mfma_f32_16x16x32_bf16 v[174:177], v[130:133], v[162:165], v[174:177]
	v_mfma_f32_16x16x32_bf16 v[114:117], v[126:129], v[170:173], v[114:117]
	v_mfma_f32_16x16x32_bf16 v[114:117], v[130:133], v[178:181], v[114:117]
	v_mfma_f32_16x16x32_bf16 v[98:101], v[126:129], v[182:185], v[98:101]
	v_mfma_f32_16x16x32_bf16 v[98:101], v[130:133], v[186:189], v[98:101]
	v_mfma_f32_16x16x32_bf16 v[82:85], v[126:129], v[190:193], v[82:85]
	v_mfma_f32_16x16x32_bf16 v[82:85], v[130:133], v[210:213], v[82:85]
	v_mfma_f32_16x16x32_bf16 v[166:169], v[134:137], v[158:161], v[166:169]
	v_mfma_f32_16x16x32_bf16 v[166:169], v[138:141], v[162:165], v[166:169]
	v_mfma_f32_16x16x32_bf16 v[110:113], v[134:137], v[170:173], v[110:113]
	v_mfma_f32_16x16x32_bf16 v[110:113], v[138:141], v[178:181], v[110:113]
	v_mfma_f32_16x16x32_bf16 v[94:97], v[134:137], v[182:185], v[94:97]
	v_mfma_f32_16x16x32_bf16 v[94:97], v[138:141], v[186:189], v[94:97]
	v_mfma_f32_16x16x32_bf16 v[78:81], v[134:137], v[190:193], v[78:81]
	v_mfma_f32_16x16x32_bf16 v[78:81], v[138:141], v[210:213], v[78:81]
	v_mfma_f32_16x16x32_bf16 v[122:125], v[142:145], v[158:161], v[122:125]
	v_mfma_f32_16x16x32_bf16 v[122:125], v[146:149], v[162:165], v[122:125]
	v_mfma_f32_16x16x32_bf16 v[106:109], v[142:145], v[170:173], v[106:109]
	v_mfma_f32_16x16x32_bf16 v[106:109], v[146:149], v[178:181], v[106:109]
	v_mfma_f32_16x16x32_bf16 v[90:93], v[142:145], v[182:185], v[90:93]
	v_mfma_f32_16x16x32_bf16 v[90:93], v[146:149], v[186:189], v[90:93]
	v_mfma_f32_16x16x32_bf16 v[74:77], v[142:145], v[190:193], v[74:77]
	v_mfma_f32_16x16x32_bf16 v[74:77], v[146:149], v[210:213], v[74:77]
	v_mfma_f32_16x16x32_bf16 v[118:121], v[150:153], v[158:161], v[118:121]
	v_mfma_f32_16x16x32_bf16 v[118:121], v[154:157], v[162:165], v[118:121]
	v_mfma_f32_16x16x32_bf16 v[102:105], v[150:153], v[170:173], v[102:105]
	v_mfma_f32_16x16x32_bf16 v[102:105], v[154:157], v[178:181], v[102:105]
	v_mfma_f32_16x16x32_bf16 v[86:89], v[150:153], v[182:185], v[86:89]
	v_mfma_f32_16x16x32_bf16 v[86:89], v[154:157], v[186:189], v[86:89]
	v_mfma_f32_16x16x32_bf16 v[70:73], v[150:153], v[190:193], v[70:73]
	v_mfma_f32_16x16x32_bf16 v[70:73], v[154:157], v[210:213], v[70:73]
	s_barrier
; #define PG8_STAGE(bufoff, gbase, voff) do { _Pragma("unroll") for (int _i = 0; _i < 2; ++_i) \
;         __builtin_amdgcn_global_load_lds((const unsigned*)((const char*)(gbase) + (voff)[_i]), (PG8_LAS unsigned*)(lds + (bufoff) + ldsw + _i * 8192), 16, 0, 0); } while (0)
; #define PG8_LDA(dst, b, h) do { _Pragma("unroll") for (int m = 0; m < 4; ++m) _Pragma("unroll") for (int k = 0; k < 2; ++k) dst[m][k] = *(const PG8_LAS bf16x8*)(lds + PG8_SA(b, h) + aoff + m * 2048 + k * 1024); } while (0)
; #define PG8_LDB(dst, b, h) do { _Pragma("unroll") for (int n = 0; n < 2; ++n) _Pragma("unroll") for (int k = 0; k < 2; ++k) dst[n][k] = *(const PG8_LAS bf16x8*)(lds + PG8_SB(b, h) + boff + n * 2048 + k * 1024); } while (0)
; #define PG8_MMA(ai, bj, At, Bt) do { __builtin_amdgcn_s_setprio(1); _Pragma("unroll") for (int m = 0; m < 4; ++m) _Pragma("unroll") for (int n = 0; n < 2; ++n) _Pragma("unroll") for (int k = 0; k < 2; ++k) \
;         acc[ai][bj][m][n] = __builtin_amdgcn_mfma_f32_16x16x32_bf16(Bt[n][k], At[m][k], acc[ai][bj][m][n], 0, 0, 0); __builtin_amdgcn_s_setprio(0); } while (0)
; #define PG8_WAIT_V(n) asm volatile("s_waitcnt vmcnt(" #n ")" ::: "memory")
; #define PG8_WAIT_L(n) asm volatile("s_waitcnt lgkmcnt(" #n ")" ::: "memory")
; #define PG8_BAR __builtin_amdgcn_s_barrier()
; #define PG8_SCHED __builtin_amdgcn_sched_barrier(0)
; template <class Epi, class Sched, bool ALIGN_EPI = false, bool SP2 = false>
; __device__ __forceinline__ void gemm_phase(PG8_LAS unsigned char* lds, const Gemm g, const Sched& S, const Epi& E, const int tid_in) {
;     ...
;             PG8_LDA(At, 0, 1); PG8_STAGE(PG8_SB(0, 0), b2, voffB); PG8_STAGE(PG8_SB(0, 1), b2 + hstep, voffB); PG8_STAGE(PG8_SA(0, 0), a2, voffA);
;             PG8_WAIT_V(8); PG8_WAIT_L(0); PG8_BAR; PG8_MMA(1, 0, At, B0); PG8_MMA(1, 1, At, B1); PG8_BAR; PG8_SCHED;
;             PG8_LDB(B0, 1, 0); PG8_LDB(B1, 1, 1); PG8_SCHED; PG8_LDA(At, 1, 0); PG8_STAGE(PG8_SA(0, 1), a2 + hstep, voffA);
;             PG8_WAIT_V(8); PG8_WAIT_L(0); PG8_BAR; PG8_MMA(0, 0, At, B0); PG8_MMA(0, 1, At, B1); PG8_BAR; PG8_SCHED;
	s_add_i32 s54, s54, s17
	v_lshl_add_u64 v[214:215], s[52:53], 0, v[202:203]
	s_mov_b32 m0, s54
	ds_read_b128 v[158:161], v249 offset:16384
	ds_read_b128 v[162:165], v249 offset:17408
	ds_read_b128 v[170:173], v249 offset:18432
	ds_read_b128 v[178:181], v249 offset:19456
	ds_read_b128 v[182:185], v249 offset:20480
	ds_read_b128 v[186:189], v249 offset:21504
	ds_read_b128 v[190:193], v249 offset:22528
	ds_read_b128 v[210:213], v249 offset:23552
	global_load_lds_dwordx4 v[214:215], off
	s_add_i32 m0, s54, 0x2000
	v_lshl_add_u64 v[216:217], s[52:53], 0, v[198:199]
	s_add_u32 s52, s52, s62
	s_addc_u32 s53, s53, 0
	s_add_i32 s54, s55, s17
	global_load_lds_dwordx4 v[216:217], off
	v_lshl_add_u64 v[218:219], s[52:53], 0, v[202:203]
	s_mov_b32 m0, s54
	v_lshl_add_u64 v[220:221], s[52:53], 0, v[198:199]
	global_load_lds_dwordx4 v[218:219], off
	s_add_i32 m0, s54, 0x2000
	v_lshl_add_u64 v[222:223], s[12:13], 0, v[204:205]
	global_load_lds_dwordx4 v[220:221], off
	s_mov_b32 m0, s18
	v_lshl_add_u64 v[224:225], s[12:13], 0, v[200:201]
	global_load_lds_dwordx4 v[222:223], off
	s_mov_b32 m0, s19
	s_nop 0
	global_load_lds_dwordx4 v[224:225], off
	s_waitcnt vmcnt(8)
	s_waitcnt lgkmcnt(0)
	s_barrier
	v_mfma_f32_16x16x32_bf16 v[66:69], v[126:129], v[158:161], v[66:69]
	v_mfma_f32_16x16x32_bf16 v[66:69], v[130:133], v[162:165], v[66:69]
	v_mfma_f32_16x16x32_bf16 v[50:53], v[126:129], v[170:173], v[50:53]
	v_mfma_f32_16x16x32_bf16 v[50:53], v[130:133], v[178:181], v[50:53]
	v_mfma_f32_16x16x32_bf16 v[34:37], v[126:129], v[182:185], v[34:37]
	v_mfma_f32_16x16x32_bf16 v[34:37], v[130:133], v[186:189], v[34:37]
	v_mfma_f32_16x16x32_bf16 v[18:21], v[126:129], v[190:193], v[18:21]
	v_mfma_f32_16x16x32_bf16 v[18:21], v[130:133], v[210:213], v[18:21]
	v_mfma_f32_16x16x32_bf16 v[62:65], v[134:137], v[158:161], v[62:65]
	v_mfma_f32_16x16x32_bf16 v[62:65], v[138:141], v[162:165], v[62:65]
	v_mfma_f32_16x16x32_bf16 v[46:49], v[134:137], v[170:173], v[46:49]
	v_mfma_f32_16x16x32_bf16 v[46:49], v[138:141], v[178:181], v[46:49]
	v_mfma_f32_16x16x32_bf16 v[30:33], v[134:137], v[182:185], v[30:33]
	v_mfma_f32_16x16x32_bf16 v[30:33], v[138:141], v[186:189], v[30:33]
	v_mfma_f32_16x16x32_bf16 v[14:17], v[134:137], v[190:193], v[14:17]
	v_mfma_f32_16x16x32_bf16 v[14:17], v[138:141], v[210:213], v[14:17]
	v_mfma_f32_16x16x32_bf16 v[58:61], v[142:145], v[158:161], v[58:61]
	v_mfma_f32_16x16x32_bf16 v[58:61], v[146:149], v[162:165], v[58:61]
	v_mfma_f32_16x16x32_bf16 v[42:45], v[142:145], v[170:173], v[42:45]
	v_mfma_f32_16x16x32_bf16 v[42:45], v[146:149], v[178:181], v[42:45]
	v_mfma_f32_16x16x32_bf16 v[26:29], v[142:145], v[182:185], v[26:29]
	v_mfma_f32_16x16x32_bf16 v[26:29], v[146:149], v[186:189], v[26:29]
	v_mfma_f32_16x16x32_bf16 v[10:13], v[142:145], v[190:193], v[10:13]
	v_mfma_f32_16x16x32_bf16 v[10:13], v[146:149], v[210:213], v[10:13]
	v_mfma_f32_16x16x32_bf16 v[54:57], v[150:153], v[158:161], v[54:57]
	v_mfma_f32_16x16x32_bf16 v[54:57], v[154:157], v[162:165], v[54:57]
	v_mfma_f32_16x16x32_bf16 v[38:41], v[150:153], v[170:173], v[38:41]
	v_mfma_f32_16x16x32_bf16 v[38:41], v[154:157], v[178:181], v[38:41]
	v_mfma_f32_16x16x32_bf16 v[22:25], v[150:153], v[182:185], v[22:25]
	v_mfma_f32_16x16x32_bf16 v[22:25], v[154:157], v[186:189], v[22:25]
	v_mfma_f32_16x16x32_bf16 v[6:9], v[150:153], v[190:193], v[6:9]
	v_mfma_f32_16x16x32_bf16 v[6:9], v[154:157], v[210:213], v[6:9]
	s_barrier
	s_add_i32 s52, 0, 0x18000
	s_add_i32 s53, 0, 0x1c000
	v_add_u32_e32 v138, s52, v247
	v_add_u32_e32 v154, s53, v247
	ds_read_b128 v[126:129], v138
	ds_read_b128 v[130:133], v138 offset:1024
	ds_read_b128 v[134:137], v138 offset:2048
	ds_read_b128 v[138:141], v138 offset:3072
	ds_read_b128 v[142:145], v154
	ds_read_b128 v[146:149], v154 offset:1024
	ds_read_b128 v[150:153], v154 offset:2048
	ds_read_b128 v[154:157], v154 offset:3072
	s_add_u32 s12, s12, s62
	s_addc_u32 s13, s13, 0
	s_mov_b32 m0, s22
	v_lshl_add_u64 v[226:227], s[12:13], 0, v[204:205]
	ds_read_b128 v[158:161], v249 offset:32768
	ds_read_b128 v[162:165], v249 offset:33792
	ds_read_b128 v[170:173], v249 offset:34816
	ds_read_b128 v[178:181], v249 offset:35840
	ds_read_b128 v[182:185], v249 offset:36864
	ds_read_b128 v[186:189], v249 offset:37888
	ds_read_b128 v[190:193], v249 offset:38912
	ds_read_b128 v[210:213], v249 offset:39936
	global_load_lds_dwordx4 v[226:227], off
	v_lshl_add_u64 v[226:227], s[12:13], 0, v[200:201]
	s_mov_b32 m0, s23
	s_nop 0
	global_load_lds_dwordx4 v[226:227], off
	s_waitcnt vmcnt(8)
	s_waitcnt lgkmcnt(0)
	s_barrier
; #define PG8_STAGE(bufoff, gbase, voff) do { _Pragma("unroll") for (int _i = 0; _i < 2; ++_i) \
;         __builtin_amdgcn_global_load_lds((const unsigned*)((const char*)(gbase) + (voff)[_i]), (PG8_LAS unsigned*)(lds + (bufoff) + ldsw + _i * 8192), 16, 0, 0); } while (0)
; #define PG8_LDA(dst, b, h) do { _Pragma("unroll") for (int m = 0; m < 4; ++m) _Pragma("unroll") for (int k = 0; k < 2; ++k) dst[m][k] = *(const PG8_LAS bf16x8*)(lds + PG8_SA(b, h) + aoff + m * 2048 + k * 1024); } while (0)
; #define PG8_MMA(ai, bj, At, Bt) do { __builtin_amdgcn_s_setprio(1); _Pragma("unroll") for (int m = 0; m < 4; ++m) _Pragma("unroll") for (int n = 0; n < 2; ++n) _Pragma("unroll") for (int k = 0; k < 2; ++k) \
;         acc[ai][bj][m][n] = __builtin_amdgcn_mfma_f32_16x16x32_bf16(Bt[n][k], At[m][k], acc[ai][bj][m][n], 0, 0, 0); __builtin_amdgcn_s_setprio(0); } while (0)
; #define PG8_WAIT_V(n) asm volatile("s_waitcnt vmcnt(" #n ")" ::: "memory")
; #define PG8_WAIT_L(n) asm volatile("s_waitcnt lgkmcnt(" #n ")" ::: "memory")
; #define PG8_BAR __builtin_amdgcn_s_barrier()
; #define PG8_SCHED __builtin_amdgcn_sched_barrier(0)
; template <class Epi, class Sched, bool ALIGN_EPI = false, bool SP2 = false>
; __device__ __forceinline__ void gemm_phase(PG8_LAS unsigned char* lds, const Gemm g, const Sched& S, const Epi& E, const int tid_in) {
;     ...
;             PG8_WAIT_V(8); PG8_WAIT_L(0); PG8_BAR; PG8_MMA(0, 0, At, B0); PG8_MMA(0, 1, At, B1); PG8_BAR; PG8_SCHED;
;             PG8_LDA(At, 1, 1); PG8_STAGE(PG8_SB(1, 0), b3, voffB); PG8_STAGE(PG8_SB(1, 1), b3 + hstep, voffB); PG8_STAGE(PG8_SA(1, 0), a3, voffA);
;             PG8_WAIT_V(8); PG8_WAIT_L(0); PG8_BAR; PG8_MMA(1, 0, At, B0); PG8_MMA(1, 1, At, B1); PG8_BAR; PG8_SCHED;
	v_mfma_f32_16x16x32_bf16 v[174:177], v[126:129], v[158:161], v[174:177]
	v_mfma_f32_16x16x32_bf16 v[174:177], v[130:133], v[162:165], v[174:177]
	v_mfma_f32_16x16x32_bf16 v[114:117], v[126:129], v[170:173], v[114:117]
	v_mfma_f32_16x16x32_bf16 v[114:117], v[130:133], v[178:181], v[114:117]
	v_mfma_f32_16x16x32_bf16 v[98:101], v[126:129], v[182:185], v[98:101]
	v_mfma_f32_16x16x32_bf16 v[98:101], v[130:133], v[186:189], v[98:101]
	v_mfma_f32_16x16x32_bf16 v[82:85], v[126:129], v[190:193], v[82:85]
	v_mfma_f32_16x16x32_bf16 v[82:85], v[130:133], v[210:213], v[82:85]
	v_mfma_f32_16x16x32_bf16 v[166:169], v[134:137], v[158:161], v[166:169]
	v_mfma_f32_16x16x32_bf16 v[166:169], v[138:141], v[162:165], v[166:169]
	v_mfma_f32_16x16x32_bf16 v[110:113], v[134:137], v[170:173], v[110:113]
	v_mfma_f32_16x16x32_bf16 v[110:113], v[138:141], v[178:181], v[110:113]
	v_mfma_f32_16x16x32_bf16 v[94:97], v[134:137], v[182:185], v[94:97]
	v_mfma_f32_16x16x32_bf16 v[94:97], v[138:141], v[186:189], v[94:97]
	v_mfma_f32_16x16x32_bf16 v[78:81], v[134:137], v[190:193], v[78:81]
	v_mfma_f32_16x16x32_bf16 v[78:81], v[138:141], v[210:213], v[78:81]
	v_mfma_f32_16x16x32_bf16 v[122:125], v[142:145], v[158:161], v[122:125]
	v_mfma_f32_16x16x32_bf16 v[122:125], v[146:149], v[162:165], v[122:125]
	v_mfma_f32_16x16x32_bf16 v[106:109], v[142:145], v[170:173], v[106:109]
	v_mfma_f32_16x16x32_bf16 v[106:109], v[146:149], v[178:181], v[106:109]
	v_mfma_f32_16x16x32_bf16 v[90:93], v[142:145], v[182:185], v[90:93]
	v_mfma_f32_16x16x32_bf16 v[90:93], v[146:149], v[186:189], v[90:93]
	v_mfma_f32_16x16x32_bf16 v[74:77], v[142:145], v[190:193], v[74:77]
	v_mfma_f32_16x16x32_bf16 v[74:77], v[146:149], v[210:213], v[74:77]
	v_mfma_f32_16x16x32_bf16 v[118:121], v[150:153], v[158:161], v[118:121]
	v_mfma_f32_16x16x32_bf16 v[118:121], v[154:157], v[162:165], v[118:121]
	v_mfma_f32_16x16x32_bf16 v[102:105], v[150:153], v[170:173], v[102:105]
	v_mfma_f32_16x16x32_bf16 v[102:105], v[154:157], v[178:181], v[102:105]
	v_mfma_f32_16x16x32_bf16 v[86:89], v[150:153], v[182:185], v[86:89]
	v_mfma_f32_16x16x32_bf16 v[86:89], v[154:157], v[186:189], v[86:89]
	v_mfma_f32_16x16x32_bf16 v[70:73], v[150:153], v[190:193], v[70:73]
	v_mfma_f32_16x16x32_bf16 v[70:73], v[154:157], v[210:213], v[70:73]
	s_barrier
	s_add_i32 s12, s52, s17
	v_lshl_add_u64 v[214:215], v[214:215], 0, s[28:29]
	s_mov_b32 m0, s12
	ds_read_b128 v[158:161], v249 offset:49152
	ds_read_b128 v[162:165], v249 offset:50176
	ds_read_b128 v[170:173], v249 offset:51200
	ds_read_b128 v[178:181], v249 offset:52224
	ds_read_b128 v[182:185], v249 offset:53248
	ds_read_b128 v[186:189], v249 offset:54272
	ds_read_b128 v[190:193], v249 offset:55296
	ds_read_b128 v[210:213], v249 offset:56320
	global_load_lds_dwordx4 v[214:215], off
	v_lshl_add_u64 v[214:215], v[216:217], 0, s[28:29]
	s_add_i32 m0, s12, 0x2000
	s_add_i32 s12, s53, s17
	global_load_lds_dwordx4 v[214:215], off
	v_lshl_add_u64 v[214:215], v[218:219], 0, s[28:29]
	s_mov_b32 m0, s12
	s_nop 0
	global_load_lds_dwordx4 v[214:215], off
	v_lshl_add_u64 v[214:215], v[220:221], 0, s[28:29]
	s_add_i32 m0, s12, 0x2000
	s_nop 0
	global_load_lds_dwordx4 v[214:215], off
	v_lshl_add_u64 v[214:215], v[222:223], 0, s[28:29]
	s_mov_b32 m0, s26
	s_nop 0
	global_load_lds_dwordx4 v[214:215], off
	v_lshl_add_u64 v[214:215], v[224:225], 0, s[28:29]
	s_mov_b32 m0, s27
	s_nop 0
	global_load_lds_dwordx4 v[214:215], off
	s_waitcnt vmcnt(8)
	s_waitcnt lgkmcnt(0)
	s_barrier
	v_mfma_f32_16x16x32_bf16 v[66:69], v[126:129], v[158:161], v[66:69]
	v_mfma_f32_16x16x32_bf16 v[66:69], v[130:133], v[162:165], v[66:69]
	v_mfma_f32_16x16x32_bf16 v[50:53], v[126:129], v[170:173], v[50:53]
	v_mfma_f32_16x16x32_bf16 v[50:53], v[130:133], v[178:181], v[50:53]
	v_mfma_f32_16x16x32_bf16 v[34:37], v[126:129], v[182:185], v[34:37]
	v_mfma_f32_16x16x32_bf16 v[34:37], v[130:133], v[186:189], v[34:37]
	v_mfma_f32_16x16x32_bf16 v[18:21], v[126:129], v[190:193], v[18:21]
	v_mfma_f32_16x16x32_bf16 v[18:21], v[130:133], v[210:213], v[18:21]
	v_mfma_f32_16x16x32_bf16 v[62:65], v[134:137], v[158:161], v[62:65]
	v_mfma_f32_16x16x32_bf16 v[62:65], v[138:141], v[162:165], v[62:65]
	v_mfma_f32_16x16x32_bf16 v[46:49], v[134:137], v[170:173], v[46:49]
	v_mfma_f32_16x16x32_bf16 v[46:49], v[138:141], v[178:181], v[46:49]
	v_mfma_f32_16x16x32_bf16 v[30:33], v[134:137], v[182:185], v[30:33]
	v_mfma_f32_16x16x32_bf16 v[30:33], v[138:141], v[186:189], v[30:33]
	v_mfma_f32_16x16x32_bf16 v[14:17], v[134:137], v[190:193], v[14:17]
	v_mfma_f32_16x16x32_bf16 v[14:17], v[138:141], v[210:213], v[14:17]
	v_mfma_f32_16x16x32_bf16 v[58:61], v[142:145], v[158:161], v[58:61]
	v_mfma_f32_16x16x32_bf16 v[58:61], v[146:149], v[162:165], v[58:61]
	v_mfma_f32_16x16x32_bf16 v[42:45], v[142:145], v[170:173], v[42:45]
	v_mfma_f32_16x16x32_bf16 v[42:45], v[146:149], v[178:181], v[42:45]
	v_mfma_f32_16x16x32_bf16 v[26:29], v[142:145], v[182:185], v[26:29]
	v_mfma_f32_16x16x32_bf16 v[26:29], v[146:149], v[186:189], v[26:29]
	v_mfma_f32_16x16x32_bf16 v[10:13], v[142:145], v[190:193], v[10:13]
	v_mfma_f32_16x16x32_bf16 v[10:13], v[146:149], v[210:213], v[10:13]
	v_mfma_f32_16x16x32_bf16 v[54:57], v[150:153], v[158:161], v[54:57]
	v_mfma_f32_16x16x32_bf16 v[54:57], v[154:157], v[162:165], v[54:57]
	v_mfma_f32_16x16x32_bf16 v[38:41], v[150:153], v[170:173], v[38:41]
	v_mfma_f32_16x16x32_bf16 v[38:41], v[154:157], v[178:181], v[38:41]
	v_mfma_f32_16x16x32_bf16 v[22:25], v[150:153], v[182:185], v[22:25]
	v_mfma_f32_16x16x32_bf16 v[22:25], v[154:157], v[186:189], v[22:25]
	v_mfma_f32_16x16x32_bf16 v[6:9], v[150:153], v[190:193], v[6:9]
	v_mfma_f32_16x16x32_bf16 v[6:9], v[154:157], v[210:213], v[6:9]
	s_barrier
	s_add_u32 s10, s10, 0x100
	s_addc_u32 s11, s11, 0
	s_add_u32 s14, s14, 0x100
	s_addc_u32 s15, s15, 0
	s_cmp_ge_u32 s51, s30
	s_mov_b32 s12, s51
	s_cbranch_scc0 .LBB0_177
	s_and_b64 vcc, exec, s[42:43]
	s_cbranch_vccz .LBB0_180
	s_barrier

; __device__ __forceinline__ void ssd_scan(const MixP& C, const int wg, const int nwgs, const int tid) {
;     ...
;     if (tid < per && qi < NQ) {
;         const int e = (qi & 2047) * 4, bgh = __builtin_amdgcn_readfirstlane(qi >> 11), hh = bgh & 1, bg = bgh >> 1;
;         float* dp = C.DS + ((size_t)bg * NSC * 2 + hh) * 8192 + e;
;         const float* ep = C.ESC + (size_t)bg * NSC * 2 + hh;
;         f32x4 s = {0.f, 0.f, 0.f, 0.f};
; #pragma unroll 1
;         for (int h0 = 0; h0 < NSC; h0 += NSC / 2) {
;             f32x4 d[NSC / 2]; float E[NSC / 2];
; #pragma unroll
;             for (int k = 0; k < NSC / 2; ++k) { d[k] = *(const f32x4*)(dp + (size_t)(h0 + k) * 2 * 8192); E[k] = ep[(h0 + k) * 2]; }
; #pragma unroll
;             for (int k = 0; k < NSC / 2; ++k) { *(f32x4*)(dp + (size_t)(h0 + k) * 2 * 8192) = s; s = s * E[k] + d[k]; }
;         }
;         const int b = bg >> 1, g = bg & 1;
;         *(f32x4*)(C.out + O_SSMP + (((size_t)C.l * BP + b) * 4 + 2 * g + hh) * 8192 + e) = s;
.LBB0_289:
	s_or_b64 exec, exec, s[2:3]
	s_waitcnt lgkmcnt(0)
	s_barrier
	s_mov_b64 s[72:73], exec
	v_readlane_b32 s2, v255, 44
	v_readlane_b32 s3, v255, 45
	s_and_b64 s[2:3], s[72:73], s[2:3]
	s_mov_b64 exec, s[2:3]
	s_cbranch_execz .LBB0_293
	v_readfirstlane_b32 s2, v141
	s_ashr_i32 s6, s2, 12
	s_bfe_u32 s70, s2, 0x1000b
	s_ashr_i32 s7, s6, 31
	s_mov_b32 s69, s2
	s_lshl_b64 s[2:3], s[6:7], 21
	s_lshl_b32 s4, s70, 15
	s_or_b32 s2, s2, s4
	v_lshl_add_u64 v[2:3], v[130:131], 0, s[2:3]
	s_lshl_b64 s[2:3], s[6:7], 8
	v_readlane_b32 s4, v252, 4
	s_add_u32 s2, s4, s2
	v_readlane_b32 s4, v252, 5
	s_addc_u32 s3, s4, s3
	s_lshl_b32 s4, s70, 2
	v_writelane_b32 v255, s76, 48
	s_add_u32 s9, s2, s4
	s_waitcnt vmcnt(0)
	v_mov_b32_e32 v6, 0
	v_writelane_b32 v255, s77, 49
	s_mov_b32 s75, s80
	s_mov_b32 s71, s63
	s_mov_b32 s76, s6
	s_addc_u32 s4, s3, 0
	s_mov_b32 s5, 0
	s_mov_b64 s[10:11], -1
	v_mov_b32_e32 v7, v6
	v_mov_b64_e32 v[8:9], 0
	s_mov_b32 s8, 0x10000
	s_mov_b32 s6, 0x20000
	s_mov_b32 s7, 0x30000
	s_mov_b32 s96, 0x50000
	s_mov_b32 s64, 0x70000
	s_mov_b32 s97, 0x40000
	s_mov_b32 s33, 0x60000

; __device__ __forceinline__ void ssd_scan(const MixP& C, const int wg, const int nwgs, const int tid) {
;     ...
;     if (tid < per && qi < NQ) {
;         const int e = (qi & 2047) * 4, bgh = __builtin_amdgcn_readfirstlane(qi >> 11), hh = bgh & 1, bg = bgh >> 1;
;         float* dp = C.DS + ((size_t)bg * NSC * 2 + hh) * 8192 + e;
;         const float* ep = C.ESC + (size_t)bg * NSC * 2 + hh;
;         f32x4 s = {0.f, 0.f, 0.f, 0.f};
; #pragma unroll 1
;         for (int h0 = 0; h0 < NSC; h0 += NSC / 2) {
;             f32x4 d[NSC / 2]; float E[NSC / 2];
; #pragma unroll
;             for (int k = 0; k < NSC / 2; ++k) { d[k] = *(const f32x4*)(dp + (size_t)(h0 + k) * 2 * 8192); E[k] = ep[(h0 + k) * 2]; }
; #pragma unroll
;             for (int k = 0; k < NSC / 2; ++k) { *(f32x4*)(dp + (size_t)(h0 + k) * 2 * 8192) = s; s = s * E[k] + d[k]; }
;         }
;         const int b = bg >> 1, g = bg & 1;
;         *(f32x4*)(C.out + O_SSMP + (((size_t)C.l * BP + b) * 4 + 2 * g + hh) * 8192 + e) = s;
.LBB0_312:
	s_or_b64 exec, exec, s[2:3]
	s_barrier
	s_mov_b64 s[70:71], exec
	v_readlane_b32 s2, v255, 44
	v_readlane_b32 s3, v255, 45
	s_and_b64 s[2:3], s[70:71], s[2:3]
	s_mov_b64 exec, s[2:3]
	s_cbranch_execz .LBB0_316
	v_readfirstlane_b32 s69, v141
	s_ashr_i32 s4, s69, 12
	s_bfe_u32 s6, s69, 0x1000b
	s_ashr_i32 s5, s4, 31
	s_lshl_b64 s[2:3], s[4:5], 21
	s_lshl_b32 s9, s6, 15
	s_or_b32 s2, s2, s9
	v_lshl_add_u64 v[2:3], v[130:131], 0, s[2:3]
	s_lshl_b64 s[2:3], s[4:5], 8
	v_readlane_b32 s5, v252, 4
	s_add_u32 s2, s5, s2
	v_readlane_b32 s5, v252, 5
	s_addc_u32 s3, s5, s3
	s_lshl_b32 s5, s6, 2
	v_writelane_b32 v255, s36, 48
	s_mov_b32 s7, s63
	s_add_u32 s5, s2, s5
	s_waitcnt vmcnt(0)
	v_mov_b32_e32 v6, 0
	v_writelane_b32 v255, s37, 49
	s_mov_b32 s77, s68
	s_mov_b32 s68, s75
	s_mov_b32 s75, s80
	s_mov_b32 s76, s4
	s_mov_b64 s[72:73], s[6:7]
	s_addc_u32 s9, s3, 0
	s_mov_b32 s3, 0
	s_mov_b64 s[10:11], -1
	v_mov_b32_e32 v7, v6
	v_mov_b64_e32 v[8:9], 0
	s_mov_b32 s4, 0x10000
	s_mov_b32 s6, 0x20000
	s_mov_b32 s7, 0x30000
	s_mov_b32 s96, 0x50000
	s_mov_b32 s64, 0x70000
	s_mov_b32 s97, 0x40000
	s_mov_b32 s33, 0x60000

; __device__ __forceinline__ void ssd_scan(const MixP& C, const int wg, const int nwgs, const int tid) {
;     ...
;     if (tid < per && qi < NQ) {
;         const int e = (qi & 2047) * 4, bgh = __builtin_amdgcn_readfirstlane(qi >> 11), hh = bgh & 1, bg = bgh >> 1;
;         float* dp = C.DS + ((size_t)bg * NSC * 2 + hh) * 8192 + e;
;         const float* ep = C.ESC + (size_t)bg * NSC * 2 + hh;
;         f32x4 s = {0.f, 0.f, 0.f, 0.f};
; #pragma unroll 1
;         for (int h0 = 0; h0 < NSC; h0 += NSC / 2) {
;             f32x4 d[NSC / 2]; float E[NSC / 2];
; #pragma unroll
;             for (int k = 0; k < NSC / 2; ++k) { d[k] = *(const f32x4*)(dp + (size_t)(h0 + k) * 2 * 8192); E[k] = ep[(h0 + k) * 2]; }
; #pragma unroll
;             for (int k = 0; k < NSC / 2; ++k) { *(f32x4*)(dp + (size_t)(h0 + k) * 2 * 8192) = s; s = s * E[k] + d[k]; }
;         }
;         const int b = bg >> 1, g = bg & 1;
;         *(f32x4*)(C.out + O_SSMP + (((size_t)C.l * BP + b) * 4 + 2 * g + hh) * 8192 + e) = s;
.LBB0_567:
	s_or_b64 exec, exec, s[0:1]
	v_readlane_b32 s0, v253, 7
	s_barrier
	s_nop 0
	v_add_u32_e32 v3, s0, v244
	v_readlane_b32 s0, v253, 6
	s_nop 1
	v_cmp_gt_i32_e32 vcc, s0, v244
	v_cmp_gt_i32_e64 s[0:1], s22, v3
	s_and_b64 s[0:1], vcc, s[0:1]
	s_and_saveexec_b64 s[72:73], s[0:1]
	s_cbranch_execz .LBB0_571
	v_readfirstlane_b32 s78, v3
	s_ashr_i32 s6, s78, 12
	s_bfe_u32 s76, s78, 0x1000b
	s_ashr_i32 s7, s6, 31
	s_lshl_b64 s[0:1], s[6:7], 21
	s_lshl_b32 s3, s76, 15
	v_lshlrev_b32_e32 v2, 2, v3
	s_or_b32 s0, s0, s3
	v_readlane_b32 s10, v252, 2
	v_and_b32_e32 v2, 0x1ffc, v2
	v_readlane_b32 s11, v252, 3
	s_add_u32 s0, s10, s0
	s_addc_u32 s1, s11, s1
	s_waitcnt vmcnt(0)
	v_lshlrev_b32_e32 v6, 2, v2
	v_mov_b32_e32 v7, v4
	v_lshl_add_u64 v[14:15], s[0:1], 0, v[6:7]
	s_mov_b32 s0, s6
	v_writelane_b32 v255, s0, 44
	v_readlane_b32 s3, v252, 4
	v_mov_b32_e32 v6, 0
	v_writelane_b32 v255, s1, 45
	s_lshl_b64 s[0:1], s[6:7], 8
	s_add_u32 s0, s3, s0
	v_readlane_b32 s3, v252, 5
	s_addc_u32 s1, s3, s1
	s_lshl_b32 s3, s76, 2
	s_add_u32 s9, s0, s3
	s_mov_b32 s77, s63
	s_addc_u32 s3, s1, 0
	s_mov_b32 s13, 0
	s_mov_b64 s[10:11], -1
	v_mov_b32_e32 v7, v6
	v_mov_b64_e32 v[8:9], 0
	s_mov_b32 s79, 0x20000
	s_mov_b32 s6, 0x30000
	s_mov_b32 s7, 0x40000
	s_mov_b32 s8, 0x70000
	s_mov_b32 s97, 0x60000
	s_mov_b32 s68, 0x50000

; __device__ __forceinline__ void ssd_scan(const MixP& C, const int wg, const int nwgs, const int tid) {
;     ...
;     if (tid < per && qi < NQ) {
;         const int e = (qi & 2047) * 4, bgh = __builtin_amdgcn_readfirstlane(qi >> 11), hh = bgh & 1, bg = bgh >> 1;
;         float* dp = C.DS + ((size_t)bg * NSC * 2 + hh) * 8192 + e;
;         const float* ep = C.ESC + (size_t)bg * NSC * 2 + hh;
;         f32x4 s = {0.f, 0.f, 0.f, 0.f};
; #pragma unroll 1
;         for (int h0 = 0; h0 < NSC; h0 += NSC / 2) {
;             f32x4 d[NSC / 2]; float E[NSC / 2];
; #pragma unroll
;             for (int k = 0; k < NSC / 2; ++k) { d[k] = *(const f32x4*)(dp + (size_t)(h0 + k) * 2 * 8192); E[k] = ep[(h0 + k) * 2]; }
; #pragma unroll
;             for (int k = 0; k < NSC / 2; ++k) { *(f32x4*)(dp + (size_t)(h0 + k) * 2 * 8192) = s; s = s * E[k] + d[k]; }
;         }
;         const int b = bg >> 1, g = bg & 1;
;         *(f32x4*)(C.out + O_SSMP + (((size_t)C.l * BP + b) * 4 + 2 * g + hh) * 8192 + e) = s;
.LBB0_602:
	s_or_b64 exec, exec, s[0:1]
	v_readlane_b32 s0, v253, 7
	s_waitcnt lgkmcnt(0)
	s_barrier
	v_add_u32_e32 v3, s0, v244
	v_readlane_b32 s0, v253, 6
	s_nop 1
	v_cmp_gt_i32_e32 vcc, s0, v244
	v_cmp_gt_i32_e64 s[0:1], s22, v3
	s_and_b64 s[0:1], vcc, s[0:1]
	s_and_saveexec_b64 s[72:73], s[0:1]
	s_cbranch_execz .LBB0_606
	v_readfirstlane_b32 s75, v3
	s_ashr_i32 s78, s75, 12
	s_bfe_u32 s76, s75, 0x1000b
	s_ashr_i32 s79, s78, 31
	s_lshl_b64 s[0:1], s[78:79], 21
	s_lshl_b32 s3, s76, 15
	v_lshlrev_b32_e32 v2, 2, v3
	s_or_b32 s0, s0, s3
	v_readlane_b32 s10, v252, 2
	v_and_b32_e32 v2, 0x1ffc, v2
	v_readlane_b32 s11, v252, 3
	s_add_u32 s0, s10, s0
	s_addc_u32 s1, s11, s1
	s_waitcnt vmcnt(0)
	v_lshlrev_b32_e32 v6, 2, v2
	v_mov_b32_e32 v7, v4
	v_lshl_add_u64 v[14:15], s[0:1], 0, v[6:7]
	s_lshl_b64 s[0:1], s[78:79], 8
	v_readlane_b32 s3, v252, 4
	s_add_u32 s0, s3, s0
	v_readlane_b32 s3, v252, 5
	s_addc_u32 s1, s3, s1
	s_lshl_b32 s3, s76, 2
	s_add_u32 s9, s0, s3
	v_mov_b32_e32 v6, 0
	s_mov_b32 s77, s63
	s_addc_u32 s3, s1, 0
	s_mov_b32 s13, 0
	s_mov_b64 s[10:11], -1
	v_mov_b32_e32 v7, v6
	v_mov_b64_e32 v[8:9], 0
	s_mov_b32 s79, 0x20000
	s_mov_b32 s4, 0x30000
	s_mov_b32 s5, 0x40000
	s_mov_b32 s8, 0x70000
	s_mov_b32 s97, 0x60000
	s_mov_b32 s68, 0x50000
